# v39 + rotary cos/sin vectors of all 8 row groups preloaded in the layer-0 projection epilogue, next-row prefetch in the LN3/router row loop
# baseline (speedup 1.0000x reference)
;     __device__ __forceinline__ void operator()(EPI_ARGS) const {
;         const int row0 = u.pm * BM + wr * 64 + fr; const bool rot = (u.pn >= 12 && u.pn <= 16); const int fi = 16 * wc + 4 * fq;
; #pragma unroll
;         for (int ai = 0; ai < 2; ++ai)
; #pragma unroll
;             for (int m = 0; m < 4; ++m) { const int row = row0 + ai * HALF + m * 16;
;                 f32x4 c4 = (f32x4){1.f, 1.f, 1.f, 1.f}, s4 = (f32x4){0.f, 0.f, 0.f, 0.f};
;                 if (rot) { c4 = *(const f32x4*)(cs + (size_t)row * 64 + fi); s4 = *(const f32x4*)(sn + (size_t)row * 64 + fi); }
.LBB0_1087:
	s_add_i32 s7, s6, -12
	v_lshl_add_u32 v160, s8, 8, v164
	s_cmp_lt_u32 s7, 5
	s_cselect_b64 s[36:37], -1, 0
	s_cmp_gt_u32 s7, 4
	v_ashrrev_i32_e32 v161, 31, v160
	s_cbranch_scc1 .LBB0_1089
	v_lshlrev_b64 v[128:129], 8, v[160:161]
	v_lshl_add_u64 v[130:131], v[144:145], 0, v[128:129]
	v_lshl_add_u64 v[128:129], v[146:147], 0, v[128:129]
	v_mov_b32_e32 v243, 0
	v_mov_b32_e32 v242, 0x1000
	v_lshl_add_u64 v[244:245], v[130:131], 0, v[242:243]
	global_load_dwordx4 v[178:181], v[244:245], off
	v_lshl_add_u64 v[244:245], v[128:129], 0, v[242:243]
	global_load_dwordx4 v[182:185], v[244:245], off
	v_mov_b32_e32 v242, 0x2000
	v_lshl_add_u64 v[244:245], v[130:131], 0, v[242:243]
	global_load_dwordx4 v[186:189], v[244:245], off
	v_lshl_add_u64 v[244:245], v[128:129], 0, v[242:243]
	global_load_dwordx4 v[190:193], v[244:245], off
	v_mov_b32_e32 v242, 0x3000
	v_lshl_add_u64 v[244:245], v[130:131], 0, v[242:243]
	global_load_dwordx4 v[194:197], v[244:245], off
	v_lshl_add_u64 v[244:245], v[128:129], 0, v[242:243]
	global_load_dwordx4 v[198:201], v[244:245], off
	v_mov_b32_e32 v242, 0x8000
	v_lshl_add_u64 v[244:245], v[130:131], 0, v[242:243]
	global_load_dwordx4 v[202:205], v[244:245], off
	v_lshl_add_u64 v[244:245], v[128:129], 0, v[242:243]
	global_load_dwordx4 v[206:209], v[244:245], off
	v_mov_b32_e32 v242, 0x9000
	v_lshl_add_u64 v[244:245], v[130:131], 0, v[242:243]
	global_load_dwordx4 v[210:213], v[244:245], off
	v_lshl_add_u64 v[244:245], v[128:129], 0, v[242:243]
	global_load_dwordx4 v[214:217], v[244:245], off
	v_mov_b32_e32 v242, 0xa000
	v_lshl_add_u64 v[244:245], v[130:131], 0, v[242:243]
	global_load_dwordx4 v[218:221], v[244:245], off
	v_lshl_add_u64 v[244:245], v[128:129], 0, v[242:243]
	global_load_dwordx4 v[222:225], v[244:245], off
	v_mov_b32_e32 v242, 0xb000
	v_lshl_add_u64 v[244:245], v[130:131], 0, v[242:243]
	global_load_dwordx4 v[226:229], v[244:245], off
	v_lshl_add_u64 v[244:245], v[128:129], 0, v[242:243]
	global_load_dwordx4 v[230:233], v[244:245], off
	global_load_dwordx4 v[132:135], v[130:131], off
	s_nop 0
	global_load_dwordx4 v[128:131], v[128:129], off
	s_waitcnt vmcnt(0)
	s_branch .LBB0_1090

; __device__ __forceinline__ u32x4 pack8bf(const f32x4 a, const f32x4 b) { u32x4 w; w.x = cvt_pk_bf16(a[0], a[1]); w.y = cvt_pk_bf16(a[2], a[3]); w.z = cvt_pk_bf16(b[0], b[1]); w.w = cvt_pk_bf16(b[2], b[3]); return w; }
;     __device__ __forceinline__ float qscale(const Unit& u) const { return ((u.pn >= 8 && u.pn <= 11) || u.pn == 17) ? 0.5f : 1.0f; }
;     ...
;         if constexpr (QM == 2) { const float qs0_ = g.qs * E.qscale(cur), qs1_ = qs0_ * g.qs_b1; _Pragma("unroll") for (int a = 0; a < 2; ++a) _Pragma("unroll") for (int b = 0; b < 2; ++b) _Pragma("unroll") for (int m = 0; m < 4; ++m) _Pragma("unroll") for (int n = 0; n < 2; ++n) { const v4i t_ = __builtin_bit_cast(v4i, acc[a][b][m][n]); acc[a][b][m][n] = (f32x4){(float)t_[0], (float)t_[1], (float)t_[2], (float)t_[3]} * (b == 0 ? qs0_ : qs1_); } }
;     __device__ __forceinline__ void operator()(EPI_ARGS) const {
;     ...
;                 for (int bj = 0; bj < 2; ++bj) { const int hd = 2 * u.pn + bj; const f32x4 v0 = acc[ai][bj][m][0], v1 = acc[ai][bj][m][1];
;                     const f32x4 o0 = v0 * c4 - v1 * s4, o1 = v1 * c4 + v0 * s4;
;                     *(u32x4*)(O + ((size_t)hd * NTOK + row) * 128 + 32 * wc + 8 * fq) = pack8bf(o0, o1);
;                     if (u.pn < 8) { float s = ((o0[0] * o0[0] + o0[1] * o0[1]) + (o0[2] * o0[2] + o0[3] * o0[3])) + ((o1[0] * o1[0] + o1[1] * o1[1]) + (o1[2] * o1[2] + o1[3] * o1[3]));
;                         s += __shfl_xor(s, 16); s += __shfl_xor(s, 32);
;                         if (fq == 0) nrm[((size_t)hd * NTOK + row) * 4 + wc] = s; } } }
.LBB0_1090:
	s_lshl_b32 s30, s6, 1
	s_cmp_lt_i32 s6, 8
	s_cselect_b64 s[8:9], -1, 0
	s_and_b32 s7, s6, -4
	s_cmp_eq_u32 s7, 8
	s_cselect_b64 s[28:29], -1, 0
	s_cmp_eq_u32 s6, 17
	v_cvt_f32_i32_e32 v121, v121
	v_cvt_f32_i32_e32 v123, v123
	v_cvt_f32_i32_e32 v122, v122
	v_cvt_f32_i32_e32 v120, v120
	s_cselect_b64 s[58:59], -1, 0
	v_cvt_f32_i32_e32 v127, v127
	v_cvt_f32_i32_e32 v126, v126
	v_cvt_f32_i32_e32 v125, v125
	v_cvt_f32_i32_e32 v124, v124
	s_or_b64 vcc, s[58:59], s[28:29]
	v_cndmask_b32_e32 v158, v169, v170, vcc
	s_ashr_i32 s31, s30, 31
	v_pk_mul_f32 v[122:123], v[158:159], v[122:123] op_sel_hi:[0,1]
	v_pk_mul_f32 v[120:121], v[158:159], v[120:121] op_sel_hi:[0,1]
	s_lshl_b64 s[28:29], s[30:31], 14
	v_pk_mul_f32 v[172:173], v[158:159], v[124:125] op_sel_hi:[0,1]
	v_pk_mul_f32 v[126:127], v[158:159], v[126:127] op_sel_hi:[0,1]
	v_pk_mul_f32 v[162:163], v[120:121], v[128:129]
	v_pk_mul_f32 v[124:125], v[122:123], v[130:131]
	v_pk_mul_f32 v[120:121], v[120:121], v[132:133]
	v_pk_mul_f32 v[122:123], v[122:123], v[134:135]
	v_pk_fma_f32 v[124:125], v[126:127], v[134:135], v[124:125] neg_lo:[0,0,1] neg_hi:[0,0,1]
	v_pk_fma_f32 v[122:123], v[126:127], v[130:131], v[122:123]
	v_pk_fma_f32 v[126:127], v[172:173], v[128:129], v[120:121]
	v_lshl_add_u64 v[120:121], s[28:29], 0, v[160:161]
	v_lshlrev_b64 v[176:177], 8, v[120:121]
	s_cmp_gt_i32 s6, 7
	v_pk_fma_f32 v[162:163], v[172:173], v[132:133], v[162:163] neg_lo:[0,0,1] neg_hi:[0,0,1]
	v_lshl_add_u64 v[176:177], v[148:149], 0, v[176:177]
	v_cvt_pk_bf16_f32 v172, v162, v163
	v_cvt_pk_bf16_f32 v173, v124, v125
	v_cvt_pk_bf16_f32 v174, v126, v127
	v_cvt_pk_bf16_f32 v175, v122, v123
	global_store_dwordx4 v[176:177], v[172:175], off
	s_cbranch_scc1 .LBB0_1094
	v_mul_f32_e32 v159, v163, v163
	v_mul_f32_e32 v125, v125, v125
	v_fmac_f32_e32 v159, v162, v162
	v_fmac_f32_e32 v125, v124, v124
	v_add_f32_e32 v124, v159, v125
	v_mul_f32_e32 v125, v127, v127
	v_mul_f32_e32 v123, v123, v123
	v_fmac_f32_e32 v125, v126, v126
	v_fmac_f32_e32 v123, v122, v122
	v_add_f32_e32 v122, v125, v123
	v_add_f32_e32 v122, v124, v122
	v_and_b32_e32 v124, 64, v171
	v_xor_b32_e32 v123, 16, v171
	v_add_u32_e32 v124, 64, v124
	v_cmp_lt_i32_e32 vcc, v123, v124
	s_nop 1
	v_cndmask_b32_e32 v123, v171, v123, vcc
	v_lshlrev_b32_e32 v123, 2, v123
	v_mov_b32_e32 v123, v122
	s_nop 1
	v_permlane16_swap_b32_e32 v122, v123
	s_waitcnt lgkmcnt(0)
	v_add_f32_e32 v122, v122, v123
	v_xor_b32_e32 v123, 32, v171
	v_cmp_lt_i32_e32 vcc, v123, v124
	s_nop 1
	v_cndmask_b32_e32 v123, v171, v123, vcc
	v_lshlrev_b32_e32 v123, 2, v123
	v_mov_b32_e32 v123, v122
	s_nop 1
	v_permlane32_swap_b32_e32 v122, v123
	s_and_saveexec_b64 s[6:7], s[2:3]
	s_cbranch_execz .LBB0_1093
	v_lshl_add_u64 v[120:121], v[120:121], 4, s[16:17]
	s_waitcnt lgkmcnt(0)
	v_add_f32_e32 v122, v122, v123
	global_store_dword v[120:121], v122, off

;     __device__ __forceinline__ void operator()(EPI_ARGS) const {
;     ...
;             for (int m = 0; m < 4; ++m) { const int row = row0 + ai * HALF + m * 16;
;                 f32x4 c4 = (f32x4){1.f, 1.f, 1.f, 1.f}, s4 = (f32x4){0.f, 0.f, 0.f, 0.f};
;                 if (rot) { c4 = *(const f32x4*)(cs + (size_t)row * 64 + fi); s4 = *(const f32x4*)(sn + (size_t)row * 64 + fi); }
.LBB0_1098:
	v_or_b32_e32 v120, 16, v160
	v_cndmask_b32_e64 v112, 0, 1, s[36:37]
	v_cmp_ne_u32_e64 s[8:9], 1, v112
	s_andn2_b64 vcc, exec, s[36:37]
	v_ashrrev_i32_e32 v121, 31, v120
	s_cbranch_vccnz .LBB0_1100
	v_lshlrev_b64 v[112:113], 8, v[120:121]
	s_waitcnt lgkmcnt(0)
	v_lshl_add_u64 v[114:115], v[144:145], 0, v[112:113]
	v_lshl_add_u64 v[112:113], v[146:147], 0, v[112:113]
	v_mov_b32_e32 v116, v178
	v_mov_b32_e32 v117, v179
	v_mov_b32_e32 v118, v180
	v_mov_b32_e32 v119, v181
	v_mov_b32_e32 v112, v182
	v_mov_b32_e32 v113, v183
	v_mov_b32_e32 v114, v184
	v_mov_b32_e32 v115, v185
	s_branch .LBB0_1101

; __device__ __forceinline__ u32x4 pack8bf(const f32x4 a, const f32x4 b) { u32x4 w; w.x = cvt_pk_bf16(a[0], a[1]); w.y = cvt_pk_bf16(a[2], a[3]); w.z = cvt_pk_bf16(b[0], b[1]); w.w = cvt_pk_bf16(b[2], b[3]); return w; }
;     __device__ __forceinline__ void operator()(EPI_ARGS) const {
;     ...
;                 for (int bj = 0; bj < 2; ++bj) { const int hd = 2 * u.pn + bj; const f32x4 v0 = acc[ai][bj][m][0], v1 = acc[ai][bj][m][1];
;                     const f32x4 o0 = v0 * c4 - v1 * s4, o1 = v1 * c4 + v0 * s4;
;                     *(u32x4*)(O + ((size_t)hd * NTOK + row) * 128 + 32 * wc + 8 * fq) = pack8bf(o0, o1);
;                     if (u.pn < 8) { float s = ((o0[0] * o0[0] + o0[1] * o0[1]) + (o0[2] * o0[2] + o0[3] * o0[3])) + ((o1[0] * o1[0] + o1[1] * o1[1]) + (o1[2] * o1[2] + o1[3] * o1[3]));
;                         s += __shfl_xor(s, 16); s += __shfl_xor(s, 32);
;                         if (fq == 0) nrm[((size_t)hd * NTOK + row) * 4 + wc] = s; } } }
.LBB0_1101:
	v_cvt_f32_i32_e32 v105, v105
	v_cvt_f32_i32_e32 v104, v104
	v_cvt_f32_i32_e32 v123, v109
	v_cvt_f32_i32_e32 v122, v108
	v_cvt_f32_i32_e32 v107, v107
	v_cvt_f32_i32_e32 v106, v106
	v_cvt_f32_i32_e32 v111, v111
	v_cvt_f32_i32_e32 v110, v110
	v_pk_mul_f32 v[104:105], v[158:159], v[104:105]
	v_mov_b32_e32 v108, v158
	v_mov_b32_e32 v109, v158
	v_pk_mul_f32 v[122:123], v[158:159], v[122:123]
	v_pk_mul_f32 v[124:125], v[104:105], v[112:113]
	v_pk_mul_f32 v[104:105], v[104:105], v[116:117]
	v_pk_mul_f32 v[106:107], v[108:109], v[106:107]
	v_pk_fma_f32 v[124:125], v[122:123], v[116:117], v[124:125] neg_lo:[0,0,1] neg_hi:[0,0,1]
	v_pk_fma_f32 v[122:123], v[122:123], v[112:113], v[104:105]
	v_lshl_add_u64 v[104:105], s[28:29], 0, v[120:121]
	v_pk_mul_f32 v[126:127], v[108:109], v[110:111]
	v_pk_mul_f32 v[110:111], v[106:107], v[114:115]
	v_pk_mul_f32 v[106:107], v[106:107], v[118:119]
	v_lshlrev_b64 v[130:131], 8, v[104:105]
	v_pk_fma_f32 v[110:111], v[126:127], v[118:119], v[110:111] neg_lo:[0,0,1] neg_hi:[0,0,1]
	v_pk_fma_f32 v[106:107], v[126:127], v[114:115], v[106:107]
	v_lshl_add_u64 v[130:131], v[148:149], 0, v[130:131]
	s_and_b64 vcc, exec, s[6:7]
	v_cvt_pk_bf16_f32 v126, v124, v125
	v_cvt_pk_bf16_f32 v127, v110, v111
	v_cvt_pk_bf16_f32 v128, v122, v123
	v_cvt_pk_bf16_f32 v129, v106, v107
	global_store_dwordx4 v[130:131], v[126:129], off
	s_cbranch_vccnz .LBB0_1105
	v_mul_f32_e32 v125, v125, v125
	v_mul_f32_e32 v111, v111, v111
	v_fmac_f32_e32 v125, v124, v124
	v_fmac_f32_e32 v111, v110, v110
	v_add_f32_e32 v110, v125, v111
	v_mul_f32_e32 v111, v123, v123
	v_mul_f32_e32 v107, v107, v107
	v_fmac_f32_e32 v111, v122, v122
	v_fmac_f32_e32 v107, v106, v106
	v_add_f32_e32 v106, v111, v107
	v_add_f32_e32 v106, v110, v106
	v_and_b32_e32 v110, 64, v171
	v_xor_b32_e32 v107, 16, v171
	v_add_u32_e32 v110, 64, v110
	v_cmp_lt_i32_e32 vcc, v107, v110
	s_nop 1
	v_cndmask_b32_e32 v107, v171, v107, vcc
	v_lshlrev_b32_e32 v107, 2, v107
	v_mov_b32_e32 v107, v106
	s_nop 1
	v_permlane16_swap_b32_e32 v106, v107
	s_waitcnt lgkmcnt(0)
	v_add_f32_e32 v106, v106, v107
	v_xor_b32_e32 v107, 32, v171
	v_cmp_lt_i32_e32 vcc, v107, v110
	s_nop 1
	v_cndmask_b32_e32 v107, v171, v107, vcc
	v_lshlrev_b32_e32 v107, 2, v107
	v_mov_b32_e32 v107, v106
	s_nop 1
	v_permlane32_swap_b32_e32 v106, v107
	s_and_saveexec_b64 s[36:37], s[2:3]
	s_cbranch_execz .LBB0_1104
	v_lshl_add_u64 v[104:105], v[104:105], 4, s[16:17]
	s_waitcnt lgkmcnt(0)
	v_add_f32_e32 v106, v106, v107
	global_store_dword v[104:105], v106, off

;     __device__ __forceinline__ void operator()(EPI_ARGS) const {
;     ...
;             for (int m = 0; m < 4; ++m) { const int row = row0 + ai * HALF + m * 16;
;                 f32x4 c4 = (f32x4){1.f, 1.f, 1.f, 1.f}, s4 = (f32x4){0.f, 0.f, 0.f, 0.f};
;                 if (rot) { c4 = *(const f32x4*)(cs + (size_t)row * 64 + fi); s4 = *(const f32x4*)(sn + (size_t)row * 64 + fi); }
.LBB0_1109:
	v_or_b32_e32 v104, 32, v160
	s_and_b64 vcc, exec, s[8:9]
	v_ashrrev_i32_e32 v105, 31, v104
	s_cbranch_vccnz .LBB0_1111
	v_lshlrev_b64 v[96:97], 8, v[104:105]
	s_waitcnt lgkmcnt(0)
	v_lshl_add_u64 v[98:99], v[144:145], 0, v[96:97]
	v_lshl_add_u64 v[96:97], v[146:147], 0, v[96:97]
	v_mov_b32_e32 v100, v186
	v_mov_b32_e32 v101, v187
	v_mov_b32_e32 v102, v188
	v_mov_b32_e32 v103, v189
	v_mov_b32_e32 v96, v190
	v_mov_b32_e32 v97, v191
	v_mov_b32_e32 v98, v192
	v_mov_b32_e32 v99, v193
	s_branch .LBB0_1112

; __device__ __forceinline__ u32x4 pack8bf(const f32x4 a, const f32x4 b) { u32x4 w; w.x = cvt_pk_bf16(a[0], a[1]); w.y = cvt_pk_bf16(a[2], a[3]); w.z = cvt_pk_bf16(b[0], b[1]); w.w = cvt_pk_bf16(b[2], b[3]); return w; }
;     __device__ __forceinline__ void operator()(EPI_ARGS) const {
;     ...
;                 for (int bj = 0; bj < 2; ++bj) { const int hd = 2 * u.pn + bj; const f32x4 v0 = acc[ai][bj][m][0], v1 = acc[ai][bj][m][1];
;                     const f32x4 o0 = v0 * c4 - v1 * s4, o1 = v1 * c4 + v0 * s4;
;                     *(u32x4*)(O + ((size_t)hd * NTOK + row) * 128 + 32 * wc + 8 * fq) = pack8bf(o0, o1);
;                     if (u.pn < 8) { float s = ((o0[0] * o0[0] + o0[1] * o0[1]) + (o0[2] * o0[2] + o0[3] * o0[3])) + ((o1[0] * o1[0] + o1[1] * o1[1]) + (o1[2] * o1[2] + o1[3] * o1[3]));
;                         s += __shfl_xor(s, 16); s += __shfl_xor(s, 32);
;                         if (fq == 0) nrm[((size_t)hd * NTOK + row) * 4 + wc] = s; } } }
.LBB0_1112:
	v_cvt_f32_i32_e32 v89, v89
	v_cvt_f32_i32_e32 v88, v88
	v_cvt_f32_i32_e32 v107, v93
	v_cvt_f32_i32_e32 v106, v92
	v_cvt_f32_i32_e32 v91, v91
	v_cvt_f32_i32_e32 v90, v90
	v_cvt_f32_i32_e32 v95, v95
	v_cvt_f32_i32_e32 v94, v94
	v_pk_mul_f32 v[88:89], v[158:159], v[88:89]
	v_mov_b32_e32 v92, v158
	v_mov_b32_e32 v93, v158
	v_pk_mul_f32 v[106:107], v[158:159], v[106:107]
	v_pk_mul_f32 v[108:109], v[88:89], v[96:97]
	v_pk_mul_f32 v[88:89], v[88:89], v[100:101]
	v_pk_mul_f32 v[90:91], v[92:93], v[90:91]
	v_pk_fma_f32 v[108:109], v[106:107], v[100:101], v[108:109] neg_lo:[0,0,1] neg_hi:[0,0,1]
	v_pk_fma_f32 v[106:107], v[106:107], v[96:97], v[88:89]
	v_lshl_add_u64 v[88:89], s[28:29], 0, v[104:105]
	v_pk_mul_f32 v[110:111], v[92:93], v[94:95]
	v_pk_mul_f32 v[94:95], v[90:91], v[98:99]
	v_pk_mul_f32 v[90:91], v[90:91], v[102:103]
	v_lshlrev_b64 v[114:115], 8, v[88:89]
	v_pk_fma_f32 v[94:95], v[110:111], v[102:103], v[94:95] neg_lo:[0,0,1] neg_hi:[0,0,1]
	v_pk_fma_f32 v[90:91], v[110:111], v[98:99], v[90:91]
	v_lshl_add_u64 v[114:115], v[148:149], 0, v[114:115]
	s_and_b64 vcc, exec, s[6:7]
	v_cvt_pk_bf16_f32 v110, v108, v109
	v_cvt_pk_bf16_f32 v111, v94, v95
	v_cvt_pk_bf16_f32 v112, v106, v107
	v_cvt_pk_bf16_f32 v113, v90, v91
	global_store_dwordx4 v[114:115], v[110:113], off
	s_cbranch_vccnz .LBB0_1116
	v_mul_f32_e32 v109, v109, v109
	v_mul_f32_e32 v95, v95, v95
	v_fmac_f32_e32 v109, v108, v108
	v_fmac_f32_e32 v95, v94, v94
	v_add_f32_e32 v94, v109, v95
	v_mul_f32_e32 v95, v107, v107
	v_mul_f32_e32 v91, v91, v91
	v_fmac_f32_e32 v95, v106, v106
	v_fmac_f32_e32 v91, v90, v90
	v_add_f32_e32 v90, v95, v91
	v_add_f32_e32 v90, v94, v90
	v_and_b32_e32 v94, 64, v171
	v_xor_b32_e32 v91, 16, v171
	v_add_u32_e32 v94, 64, v94
	v_cmp_lt_i32_e32 vcc, v91, v94
	s_nop 1
	v_cndmask_b32_e32 v91, v171, v91, vcc
	v_lshlrev_b32_e32 v91, 2, v91
	v_mov_b32_e32 v91, v90
	s_nop 1
	v_permlane16_swap_b32_e32 v90, v91
	s_waitcnt lgkmcnt(0)
	v_add_f32_e32 v90, v90, v91
	v_xor_b32_e32 v91, 32, v171
	v_cmp_lt_i32_e32 vcc, v91, v94
	s_nop 1
	v_cndmask_b32_e32 v91, v171, v91, vcc
	v_lshlrev_b32_e32 v91, 2, v91
	v_mov_b32_e32 v91, v90
	s_nop 1
	v_permlane32_swap_b32_e32 v90, v91
	s_and_saveexec_b64 s[36:37], s[2:3]
	s_cbranch_execz .LBB0_1115
	v_lshl_add_u64 v[88:89], v[88:89], 4, s[16:17]
	s_waitcnt lgkmcnt(0)
	v_add_f32_e32 v90, v90, v91
	global_store_dword v[88:89], v90, off

;     __device__ __forceinline__ void operator()(EPI_ARGS) const {
;     ...
;             for (int m = 0; m < 4; ++m) { const int row = row0 + ai * HALF + m * 16;
;                 f32x4 c4 = (f32x4){1.f, 1.f, 1.f, 1.f}, s4 = (f32x4){0.f, 0.f, 0.f, 0.f};
;                 if (rot) { c4 = *(const f32x4*)(cs + (size_t)row * 64 + fi); s4 = *(const f32x4*)(sn + (size_t)row * 64 + fi); }
.LBB0_1120:
	v_or_b32_e32 v88, 48, v160
	s_and_b64 vcc, exec, s[8:9]
	v_ashrrev_i32_e32 v89, 31, v88
	s_cbranch_vccnz .LBB0_1122
	v_lshlrev_b64 v[80:81], 8, v[88:89]
	s_waitcnt lgkmcnt(0)
	v_lshl_add_u64 v[82:83], v[144:145], 0, v[80:81]
	v_lshl_add_u64 v[80:81], v[146:147], 0, v[80:81]
	v_mov_b32_e32 v84, v194
	v_mov_b32_e32 v85, v195
	v_mov_b32_e32 v86, v196
	v_mov_b32_e32 v87, v197
	v_mov_b32_e32 v80, v198
	v_mov_b32_e32 v81, v199
	v_mov_b32_e32 v82, v200
	v_mov_b32_e32 v83, v201
	s_branch .LBB0_1123

; __device__ __forceinline__ u32x4 pack8bf(const f32x4 a, const f32x4 b) { u32x4 w; w.x = cvt_pk_bf16(a[0], a[1]); w.y = cvt_pk_bf16(a[2], a[3]); w.z = cvt_pk_bf16(b[0], b[1]); w.w = cvt_pk_bf16(b[2], b[3]); return w; }
;     __device__ __forceinline__ void operator()(EPI_ARGS) const {
;     ...
;                 for (int bj = 0; bj < 2; ++bj) { const int hd = 2 * u.pn + bj; const f32x4 v0 = acc[ai][bj][m][0], v1 = acc[ai][bj][m][1];
;                     const f32x4 o0 = v0 * c4 - v1 * s4, o1 = v1 * c4 + v0 * s4;
;                     *(u32x4*)(O + ((size_t)hd * NTOK + row) * 128 + 32 * wc + 8 * fq) = pack8bf(o0, o1);
;                     if (u.pn < 8) { float s = ((o0[0] * o0[0] + o0[1] * o0[1]) + (o0[2] * o0[2] + o0[3] * o0[3])) + ((o1[0] * o1[0] + o1[1] * o1[1]) + (o1[2] * o1[2] + o1[3] * o1[3]));
;                         s += __shfl_xor(s, 16); s += __shfl_xor(s, 32);
;                         if (fq == 0) nrm[((size_t)hd * NTOK + row) * 4 + wc] = s; } } }
.LBB0_1123:
	v_cvt_f32_i32_e32 v73, v73
	v_cvt_f32_i32_e32 v72, v72
	v_cvt_f32_i32_e32 v91, v77
	v_cvt_f32_i32_e32 v90, v76
	v_cvt_f32_i32_e32 v75, v75
	v_cvt_f32_i32_e32 v74, v74
	v_cvt_f32_i32_e32 v79, v79
	v_cvt_f32_i32_e32 v78, v78
	v_pk_mul_f32 v[72:73], v[158:159], v[72:73]
	v_mov_b32_e32 v76, v158
	v_mov_b32_e32 v77, v158
	v_pk_mul_f32 v[90:91], v[158:159], v[90:91]
	v_pk_mul_f32 v[92:93], v[72:73], v[80:81]
	v_pk_mul_f32 v[72:73], v[72:73], v[84:85]
	v_pk_mul_f32 v[74:75], v[76:77], v[74:75]
	v_pk_fma_f32 v[92:93], v[90:91], v[84:85], v[92:93] neg_lo:[0,0,1] neg_hi:[0,0,1]
	v_pk_fma_f32 v[90:91], v[90:91], v[80:81], v[72:73]
	v_lshl_add_u64 v[72:73], s[28:29], 0, v[88:89]
	v_pk_mul_f32 v[94:95], v[76:77], v[78:79]
	v_pk_mul_f32 v[78:79], v[74:75], v[82:83]
	v_pk_mul_f32 v[74:75], v[74:75], v[86:87]
	v_lshlrev_b64 v[98:99], 8, v[72:73]
	v_pk_fma_f32 v[78:79], v[94:95], v[86:87], v[78:79] neg_lo:[0,0,1] neg_hi:[0,0,1]
	v_pk_fma_f32 v[74:75], v[94:95], v[82:83], v[74:75]
	v_lshl_add_u64 v[98:99], v[148:149], 0, v[98:99]
	s_and_b64 vcc, exec, s[6:7]
	v_cvt_pk_bf16_f32 v94, v92, v93
	v_cvt_pk_bf16_f32 v95, v78, v79
	v_cvt_pk_bf16_f32 v96, v90, v91
	v_cvt_pk_bf16_f32 v97, v74, v75
	global_store_dwordx4 v[98:99], v[94:97], off
	s_cbranch_vccnz .LBB0_1127
	v_mul_f32_e32 v93, v93, v93
	v_mul_f32_e32 v79, v79, v79
	v_fmac_f32_e32 v93, v92, v92
	v_fmac_f32_e32 v79, v78, v78
	v_add_f32_e32 v78, v93, v79
	v_mul_f32_e32 v79, v91, v91
	v_mul_f32_e32 v75, v75, v75
	v_fmac_f32_e32 v79, v90, v90
	v_fmac_f32_e32 v75, v74, v74
	v_add_f32_e32 v74, v79, v75
	v_add_f32_e32 v74, v78, v74
	v_and_b32_e32 v78, 64, v171
	v_xor_b32_e32 v75, 16, v171
	v_add_u32_e32 v78, 64, v78
	v_cmp_lt_i32_e32 vcc, v75, v78
	s_nop 1
	v_cndmask_b32_e32 v75, v171, v75, vcc
	v_lshlrev_b32_e32 v75, 2, v75
	v_mov_b32_e32 v75, v74
	s_nop 1
	v_permlane16_swap_b32_e32 v74, v75
	s_waitcnt lgkmcnt(0)
	v_add_f32_e32 v74, v74, v75
	v_xor_b32_e32 v75, 32, v171
	v_cmp_lt_i32_e32 vcc, v75, v78
	s_nop 1
	v_cndmask_b32_e32 v75, v171, v75, vcc
	v_lshlrev_b32_e32 v75, 2, v75
	v_mov_b32_e32 v75, v74
	s_nop 1
	v_permlane32_swap_b32_e32 v74, v75
	s_and_saveexec_b64 s[36:37], s[2:3]
	s_cbranch_execz .LBB0_1126
	v_lshl_add_u64 v[72:73], v[72:73], 4, s[16:17]
	s_waitcnt lgkmcnt(0)
	v_add_f32_e32 v74, v74, v75
	global_store_dword v[72:73], v74, off

;     __device__ __forceinline__ void operator()(EPI_ARGS) const {
;     ...
;             for (int m = 0; m < 4; ++m) { const int row = row0 + ai * HALF + m * 16;
;                 f32x4 c4 = (f32x4){1.f, 1.f, 1.f, 1.f}, s4 = (f32x4){0.f, 0.f, 0.f, 0.f};
;                 if (rot) { c4 = *(const f32x4*)(cs + (size_t)row * 64 + fi); s4 = *(const f32x4*)(sn + (size_t)row * 64 + fi); }
.LBB0_1131:
	v_add_u32_e32 v72, 0x80, v160
	s_and_b64 vcc, exec, s[8:9]
	v_ashrrev_i32_e32 v73, 31, v72
	s_cbranch_vccnz .LBB0_1133
	v_lshlrev_b64 v[64:65], 8, v[72:73]
	s_waitcnt lgkmcnt(0)
	v_lshl_add_u64 v[66:67], v[144:145], 0, v[64:65]
	v_lshl_add_u64 v[64:65], v[146:147], 0, v[64:65]
	v_mov_b32_e32 v68, v202
	v_mov_b32_e32 v69, v203
	v_mov_b32_e32 v70, v204
	v_mov_b32_e32 v71, v205
	v_mov_b32_e32 v64, v206
	v_mov_b32_e32 v65, v207
	v_mov_b32_e32 v66, v208
	v_mov_b32_e32 v67, v209
	s_branch .LBB0_1134

; __device__ __forceinline__ u32x4 pack8bf(const f32x4 a, const f32x4 b) { u32x4 w; w.x = cvt_pk_bf16(a[0], a[1]); w.y = cvt_pk_bf16(a[2], a[3]); w.z = cvt_pk_bf16(b[0], b[1]); w.w = cvt_pk_bf16(b[2], b[3]); return w; }
;     __device__ __forceinline__ void operator()(EPI_ARGS) const {
;     ...
;                 for (int bj = 0; bj < 2; ++bj) { const int hd = 2 * u.pn + bj; const f32x4 v0 = acc[ai][bj][m][0], v1 = acc[ai][bj][m][1];
;                     const f32x4 o0 = v0 * c4 - v1 * s4, o1 = v1 * c4 + v0 * s4;
;                     *(u32x4*)(O + ((size_t)hd * NTOK + row) * 128 + 32 * wc + 8 * fq) = pack8bf(o0, o1);
;                     if (u.pn < 8) { float s = ((o0[0] * o0[0] + o0[1] * o0[1]) + (o0[2] * o0[2] + o0[3] * o0[3])) + ((o1[0] * o1[0] + o1[1] * o1[1]) + (o1[2] * o1[2] + o1[3] * o1[3]));
;                         s += __shfl_xor(s, 16); s += __shfl_xor(s, 32);
;                         if (fq == 0) nrm[((size_t)hd * NTOK + row) * 4 + wc] = s; } } }
.LBB0_1134:
	v_cvt_f32_i32_e32 v57, v57
	v_cvt_f32_i32_e32 v56, v56
	v_cvt_f32_i32_e32 v75, v61
	v_cvt_f32_i32_e32 v74, v60
	v_cvt_f32_i32_e32 v59, v59
	v_cvt_f32_i32_e32 v58, v58
	v_cvt_f32_i32_e32 v63, v63
	v_cvt_f32_i32_e32 v62, v62
	v_pk_mul_f32 v[56:57], v[158:159], v[56:57]
	v_mov_b32_e32 v60, v158
	v_mov_b32_e32 v61, v158
	v_pk_mul_f32 v[74:75], v[158:159], v[74:75]
	v_pk_mul_f32 v[76:77], v[56:57], v[64:65]
	v_pk_mul_f32 v[56:57], v[56:57], v[68:69]
	v_pk_mul_f32 v[58:59], v[60:61], v[58:59]
	v_pk_fma_f32 v[76:77], v[74:75], v[68:69], v[76:77] neg_lo:[0,0,1] neg_hi:[0,0,1]
	v_pk_fma_f32 v[74:75], v[74:75], v[64:65], v[56:57]
	v_lshl_add_u64 v[56:57], s[28:29], 0, v[72:73]
	v_pk_mul_f32 v[78:79], v[60:61], v[62:63]
	v_pk_mul_f32 v[62:63], v[58:59], v[66:67]
	v_pk_mul_f32 v[58:59], v[58:59], v[70:71]
	v_lshlrev_b64 v[82:83], 8, v[56:57]
	v_pk_fma_f32 v[62:63], v[78:79], v[70:71], v[62:63] neg_lo:[0,0,1] neg_hi:[0,0,1]
	v_pk_fma_f32 v[58:59], v[78:79], v[66:67], v[58:59]
	v_lshl_add_u64 v[82:83], v[148:149], 0, v[82:83]
	s_and_b64 vcc, exec, s[6:7]
	v_cvt_pk_bf16_f32 v78, v76, v77
	v_cvt_pk_bf16_f32 v79, v62, v63
	v_cvt_pk_bf16_f32 v80, v74, v75
	v_cvt_pk_bf16_f32 v81, v58, v59
	global_store_dwordx4 v[82:83], v[78:81], off
	s_cbranch_vccnz .LBB0_1138
	v_mul_f32_e32 v77, v77, v77
	v_mul_f32_e32 v63, v63, v63
	v_fmac_f32_e32 v77, v76, v76
	v_fmac_f32_e32 v63, v62, v62
	v_add_f32_e32 v62, v77, v63
	v_mul_f32_e32 v63, v75, v75
	v_mul_f32_e32 v59, v59, v59
	v_fmac_f32_e32 v63, v74, v74
	v_fmac_f32_e32 v59, v58, v58
	v_add_f32_e32 v58, v63, v59
	v_add_f32_e32 v58, v62, v58
	v_and_b32_e32 v62, 64, v171
	v_xor_b32_e32 v59, 16, v171
	v_add_u32_e32 v62, 64, v62
	v_cmp_lt_i32_e32 vcc, v59, v62
	s_nop 1
	v_cndmask_b32_e32 v59, v171, v59, vcc
	v_lshlrev_b32_e32 v59, 2, v59
	v_mov_b32_e32 v59, v58
	s_nop 1
	v_permlane16_swap_b32_e32 v58, v59
	s_waitcnt lgkmcnt(0)
	v_add_f32_e32 v58, v58, v59
	v_xor_b32_e32 v59, 32, v171
	v_cmp_lt_i32_e32 vcc, v59, v62
	s_nop 1
	v_cndmask_b32_e32 v59, v171, v59, vcc
	v_lshlrev_b32_e32 v59, 2, v59
	v_mov_b32_e32 v59, v58
	s_nop 1
	v_permlane32_swap_b32_e32 v58, v59
	s_and_saveexec_b64 s[36:37], s[2:3]
	s_cbranch_execz .LBB0_1137
	v_lshl_add_u64 v[56:57], v[56:57], 4, s[16:17]
	s_waitcnt lgkmcnt(0)
	v_add_f32_e32 v58, v58, v59
	global_store_dword v[56:57], v58, off

;     __device__ __forceinline__ void operator()(EPI_ARGS) const {
;     ...
;             for (int m = 0; m < 4; ++m) { const int row = row0 + ai * HALF + m * 16;
;                 f32x4 c4 = (f32x4){1.f, 1.f, 1.f, 1.f}, s4 = (f32x4){0.f, 0.f, 0.f, 0.f};
;                 if (rot) { c4 = *(const f32x4*)(cs + (size_t)row * 64 + fi); s4 = *(const f32x4*)(sn + (size_t)row * 64 + fi); }
.LBB0_1142:
	v_add_u32_e32 v56, 0x90, v160
	s_and_b64 vcc, exec, s[8:9]
	v_ashrrev_i32_e32 v57, 31, v56
	s_cbranch_vccnz .LBB0_1144
	v_lshlrev_b64 v[48:49], 8, v[56:57]
	s_waitcnt lgkmcnt(0)
	v_lshl_add_u64 v[50:51], v[144:145], 0, v[48:49]
	v_lshl_add_u64 v[48:49], v[146:147], 0, v[48:49]
	v_mov_b32_e32 v52, v210
	v_mov_b32_e32 v53, v211
	v_mov_b32_e32 v54, v212
	v_mov_b32_e32 v55, v213
	v_mov_b32_e32 v48, v214
	v_mov_b32_e32 v49, v215
	v_mov_b32_e32 v50, v216
	v_mov_b32_e32 v51, v217
	s_branch .LBB0_1145

; __device__ __forceinline__ u32x4 pack8bf(const f32x4 a, const f32x4 b) { u32x4 w; w.x = cvt_pk_bf16(a[0], a[1]); w.y = cvt_pk_bf16(a[2], a[3]); w.z = cvt_pk_bf16(b[0], b[1]); w.w = cvt_pk_bf16(b[2], b[3]); return w; }
;     __device__ __forceinline__ void operator()(EPI_ARGS) const {
;     ...
;                 for (int bj = 0; bj < 2; ++bj) { const int hd = 2 * u.pn + bj; const f32x4 v0 = acc[ai][bj][m][0], v1 = acc[ai][bj][m][1];
;                     const f32x4 o0 = v0 * c4 - v1 * s4, o1 = v1 * c4 + v0 * s4;
;                     *(u32x4*)(O + ((size_t)hd * NTOK + row) * 128 + 32 * wc + 8 * fq) = pack8bf(o0, o1);
;                     if (u.pn < 8) { float s = ((o0[0] * o0[0] + o0[1] * o0[1]) + (o0[2] * o0[2] + o0[3] * o0[3])) + ((o1[0] * o1[0] + o1[1] * o1[1]) + (o1[2] * o1[2] + o1[3] * o1[3]));
;                         s += __shfl_xor(s, 16); s += __shfl_xor(s, 32);
;                         if (fq == 0) nrm[((size_t)hd * NTOK + row) * 4 + wc] = s; } } }
.LBB0_1145:
	v_cvt_f32_i32_e32 v41, v41
	v_cvt_f32_i32_e32 v40, v40
	v_cvt_f32_i32_e32 v59, v45
	v_cvt_f32_i32_e32 v58, v44
	v_cvt_f32_i32_e32 v43, v43
	v_cvt_f32_i32_e32 v42, v42
	v_cvt_f32_i32_e32 v47, v47
	v_cvt_f32_i32_e32 v46, v46
	v_pk_mul_f32 v[40:41], v[158:159], v[40:41]
	v_mov_b32_e32 v44, v158
	v_mov_b32_e32 v45, v158
	v_pk_mul_f32 v[58:59], v[158:159], v[58:59]
	v_pk_mul_f32 v[60:61], v[40:41], v[48:49]
	v_pk_mul_f32 v[40:41], v[40:41], v[52:53]
	v_pk_mul_f32 v[42:43], v[44:45], v[42:43]
	v_pk_fma_f32 v[60:61], v[58:59], v[52:53], v[60:61] neg_lo:[0,0,1] neg_hi:[0,0,1]
	v_pk_fma_f32 v[58:59], v[58:59], v[48:49], v[40:41]
	v_lshl_add_u64 v[40:41], s[28:29], 0, v[56:57]
	v_pk_mul_f32 v[62:63], v[44:45], v[46:47]
	v_pk_mul_f32 v[46:47], v[42:43], v[50:51]
	v_pk_mul_f32 v[42:43], v[42:43], v[54:55]
	v_lshlrev_b64 v[66:67], 8, v[40:41]
	v_pk_fma_f32 v[46:47], v[62:63], v[54:55], v[46:47] neg_lo:[0,0,1] neg_hi:[0,0,1]
	v_pk_fma_f32 v[42:43], v[62:63], v[50:51], v[42:43]
	v_lshl_add_u64 v[66:67], v[148:149], 0, v[66:67]
	s_and_b64 vcc, exec, s[6:7]
	v_cvt_pk_bf16_f32 v62, v60, v61
	v_cvt_pk_bf16_f32 v63, v46, v47
	v_cvt_pk_bf16_f32 v64, v58, v59
	v_cvt_pk_bf16_f32 v65, v42, v43
	global_store_dwordx4 v[66:67], v[62:65], off
	s_cbranch_vccnz .LBB0_1149
	v_mul_f32_e32 v61, v61, v61
	v_mul_f32_e32 v47, v47, v47
	v_fmac_f32_e32 v61, v60, v60
	v_fmac_f32_e32 v47, v46, v46
	v_add_f32_e32 v46, v61, v47
	v_mul_f32_e32 v47, v59, v59
	v_mul_f32_e32 v43, v43, v43
	v_fmac_f32_e32 v47, v58, v58
	v_fmac_f32_e32 v43, v42, v42
	v_add_f32_e32 v42, v47, v43
	v_add_f32_e32 v42, v46, v42
	v_and_b32_e32 v46, 64, v171
	v_xor_b32_e32 v43, 16, v171
	v_add_u32_e32 v46, 64, v46
	v_cmp_lt_i32_e32 vcc, v43, v46
	s_nop 1
	v_cndmask_b32_e32 v43, v171, v43, vcc
	v_lshlrev_b32_e32 v43, 2, v43
	v_mov_b32_e32 v43, v42
	s_nop 1
	v_permlane16_swap_b32_e32 v42, v43
	s_waitcnt lgkmcnt(0)
	v_add_f32_e32 v42, v42, v43
	v_xor_b32_e32 v43, 32, v171
	v_cmp_lt_i32_e32 vcc, v43, v46
	s_nop 1
	v_cndmask_b32_e32 v43, v171, v43, vcc
	v_lshlrev_b32_e32 v43, 2, v43
	v_mov_b32_e32 v43, v42
	s_nop 1
	v_permlane32_swap_b32_e32 v42, v43
	s_and_saveexec_b64 s[36:37], s[2:3]
	s_cbranch_execz .LBB0_1148
	v_lshl_add_u64 v[40:41], v[40:41], 4, s[16:17]
	s_waitcnt lgkmcnt(0)
	v_add_f32_e32 v42, v42, v43
	global_store_dword v[40:41], v42, off

;     __device__ __forceinline__ void operator()(EPI_ARGS) const {
;     ...
;             for (int m = 0; m < 4; ++m) { const int row = row0 + ai * HALF + m * 16;
;                 f32x4 c4 = (f32x4){1.f, 1.f, 1.f, 1.f}, s4 = (f32x4){0.f, 0.f, 0.f, 0.f};
;                 if (rot) { c4 = *(const f32x4*)(cs + (size_t)row * 64 + fi); s4 = *(const f32x4*)(sn + (size_t)row * 64 + fi); }
.LBB0_1153:
	v_add_u32_e32 v40, 0xa0, v160
	s_and_b64 vcc, exec, s[8:9]
	v_ashrrev_i32_e32 v41, 31, v40
	s_cbranch_vccnz .LBB0_1155
	v_lshlrev_b64 v[32:33], 8, v[40:41]
	s_waitcnt lgkmcnt(0)
	v_lshl_add_u64 v[34:35], v[144:145], 0, v[32:33]
	v_lshl_add_u64 v[32:33], v[146:147], 0, v[32:33]
	v_mov_b32_e32 v36, v218
	v_mov_b32_e32 v37, v219
	v_mov_b32_e32 v38, v220
	v_mov_b32_e32 v39, v221
	v_mov_b32_e32 v32, v222
	v_mov_b32_e32 v33, v223
	v_mov_b32_e32 v34, v224
	v_mov_b32_e32 v35, v225
	s_branch .LBB0_1156

; __device__ __forceinline__ u32x4 pack8bf(const f32x4 a, const f32x4 b) { u32x4 w; w.x = cvt_pk_bf16(a[0], a[1]); w.y = cvt_pk_bf16(a[2], a[3]); w.z = cvt_pk_bf16(b[0], b[1]); w.w = cvt_pk_bf16(b[2], b[3]); return w; }
;     __device__ __forceinline__ void operator()(EPI_ARGS) const {
;     ...
;                 for (int bj = 0; bj < 2; ++bj) { const int hd = 2 * u.pn + bj; const f32x4 v0 = acc[ai][bj][m][0], v1 = acc[ai][bj][m][1];
;                     const f32x4 o0 = v0 * c4 - v1 * s4, o1 = v1 * c4 + v0 * s4;
;                     *(u32x4*)(O + ((size_t)hd * NTOK + row) * 128 + 32 * wc + 8 * fq) = pack8bf(o0, o1);
;                     if (u.pn < 8) { float s = ((o0[0] * o0[0] + o0[1] * o0[1]) + (o0[2] * o0[2] + o0[3] * o0[3])) + ((o1[0] * o1[0] + o1[1] * o1[1]) + (o1[2] * o1[2] + o1[3] * o1[3]));
;                         s += __shfl_xor(s, 16); s += __shfl_xor(s, 32);
;                         if (fq == 0) nrm[((size_t)hd * NTOK + row) * 4 + wc] = s; } } }
.LBB0_1156:
	v_cvt_f32_i32_e32 v25, v25
	v_cvt_f32_i32_e32 v24, v24
	v_cvt_f32_i32_e32 v43, v29
	v_cvt_f32_i32_e32 v42, v28
	v_cvt_f32_i32_e32 v27, v27
	v_cvt_f32_i32_e32 v26, v26
	v_cvt_f32_i32_e32 v31, v31
	v_cvt_f32_i32_e32 v30, v30
	v_pk_mul_f32 v[24:25], v[158:159], v[24:25]
	v_mov_b32_e32 v28, v158
	v_mov_b32_e32 v29, v158
	v_pk_mul_f32 v[42:43], v[158:159], v[42:43]
	v_pk_mul_f32 v[44:45], v[24:25], v[32:33]
	v_pk_mul_f32 v[24:25], v[24:25], v[36:37]
	v_pk_mul_f32 v[26:27], v[28:29], v[26:27]
	v_pk_fma_f32 v[44:45], v[42:43], v[36:37], v[44:45] neg_lo:[0,0,1] neg_hi:[0,0,1]
	v_pk_fma_f32 v[42:43], v[42:43], v[32:33], v[24:25]
	v_lshl_add_u64 v[24:25], s[28:29], 0, v[40:41]
	v_pk_mul_f32 v[46:47], v[28:29], v[30:31]
	v_pk_mul_f32 v[30:31], v[26:27], v[34:35]
	v_pk_mul_f32 v[26:27], v[26:27], v[38:39]
	v_lshlrev_b64 v[50:51], 8, v[24:25]
	v_pk_fma_f32 v[30:31], v[46:47], v[38:39], v[30:31] neg_lo:[0,0,1] neg_hi:[0,0,1]
	v_pk_fma_f32 v[26:27], v[46:47], v[34:35], v[26:27]
	v_lshl_add_u64 v[50:51], v[148:149], 0, v[50:51]
	s_and_b64 vcc, exec, s[6:7]
	v_cvt_pk_bf16_f32 v46, v44, v45
	v_cvt_pk_bf16_f32 v47, v30, v31
	v_cvt_pk_bf16_f32 v48, v42, v43
	v_cvt_pk_bf16_f32 v49, v26, v27
	global_store_dwordx4 v[50:51], v[46:49], off
	s_cbranch_vccnz .LBB0_1160
	v_mul_f32_e32 v45, v45, v45
	v_mul_f32_e32 v31, v31, v31
	v_fmac_f32_e32 v45, v44, v44
	v_fmac_f32_e32 v31, v30, v30
	v_add_f32_e32 v30, v45, v31
	v_mul_f32_e32 v31, v43, v43
	v_mul_f32_e32 v27, v27, v27
	v_fmac_f32_e32 v31, v42, v42
	v_fmac_f32_e32 v27, v26, v26
	v_add_f32_e32 v26, v31, v27
	v_add_f32_e32 v26, v30, v26
	v_and_b32_e32 v30, 64, v171
	v_xor_b32_e32 v27, 16, v171
	v_add_u32_e32 v30, 64, v30
	v_cmp_lt_i32_e32 vcc, v27, v30
	s_nop 1
	v_cndmask_b32_e32 v27, v171, v27, vcc
	v_lshlrev_b32_e32 v27, 2, v27
	v_mov_b32_e32 v27, v26
	s_nop 1
	v_permlane16_swap_b32_e32 v26, v27
	s_waitcnt lgkmcnt(0)
	v_add_f32_e32 v26, v26, v27
	v_xor_b32_e32 v27, 32, v171
	v_cmp_lt_i32_e32 vcc, v27, v30
	s_nop 1
	v_cndmask_b32_e32 v27, v171, v27, vcc
	v_lshlrev_b32_e32 v27, 2, v27
	v_mov_b32_e32 v27, v26
	s_nop 1
	v_permlane32_swap_b32_e32 v26, v27
	s_and_saveexec_b64 s[36:37], s[2:3]
	s_cbranch_execz .LBB0_1159
	v_lshl_add_u64 v[24:25], v[24:25], 4, s[16:17]
	s_waitcnt lgkmcnt(0)
	v_add_f32_e32 v26, v26, v27
	global_store_dword v[24:25], v26, off

;     __device__ __forceinline__ void operator()(EPI_ARGS) const {
;     ...
;             for (int m = 0; m < 4; ++m) { const int row = row0 + ai * HALF + m * 16;
;                 f32x4 c4 = (f32x4){1.f, 1.f, 1.f, 1.f}, s4 = (f32x4){0.f, 0.f, 0.f, 0.f};
;                 if (rot) { c4 = *(const f32x4*)(cs + (size_t)row * 64 + fi); s4 = *(const f32x4*)(sn + (size_t)row * 64 + fi); }
.LBB0_1164:
	v_add_u32_e32 v24, 0xb0, v160
	s_and_b64 vcc, exec, s[8:9]
	v_ashrrev_i32_e32 v25, 31, v24
	s_cbranch_vccnz .LBB0_1166
	v_lshlrev_b64 v[16:17], 8, v[24:25]
	s_waitcnt lgkmcnt(0)
	v_lshl_add_u64 v[18:19], v[144:145], 0, v[16:17]
	v_lshl_add_u64 v[16:17], v[146:147], 0, v[16:17]
	v_mov_b32_e32 v20, v226
	v_mov_b32_e32 v21, v227
	v_mov_b32_e32 v22, v228
	v_mov_b32_e32 v23, v229
	v_mov_b32_e32 v16, v230
	v_mov_b32_e32 v17, v231
	v_mov_b32_e32 v18, v232
	v_mov_b32_e32 v19, v233
	s_branch .LBB0_1167

; __device__ __forceinline__ u32x4 pack8bf(const f32x4 a, const f32x4 b) { u32x4 w; w.x = cvt_pk_bf16(a[0], a[1]); w.y = cvt_pk_bf16(a[2], a[3]); w.z = cvt_pk_bf16(b[0], b[1]); w.w = cvt_pk_bf16(b[2], b[3]); return w; }
;     __device__ __forceinline__ void operator()(EPI_ARGS) const {
;     ...
;                 for (int bj = 0; bj < 2; ++bj) { const int hd = 2 * u.pn + bj; const f32x4 v0 = acc[ai][bj][m][0], v1 = acc[ai][bj][m][1];
;                     const f32x4 o0 = v0 * c4 - v1 * s4, o1 = v1 * c4 + v0 * s4;
;                     *(u32x4*)(O + ((size_t)hd * NTOK + row) * 128 + 32 * wc + 8 * fq) = pack8bf(o0, o1);
;                     if (u.pn < 8) { float s = ((o0[0] * o0[0] + o0[1] * o0[1]) + (o0[2] * o0[2] + o0[3] * o0[3])) + ((o1[0] * o1[0] + o1[1] * o1[1]) + (o1[2] * o1[2] + o1[3] * o1[3]));
;                         s += __shfl_xor(s, 16); s += __shfl_xor(s, 32);
;                         if (fq == 0) nrm[((size_t)hd * NTOK + row) * 4 + wc] = s; } } }
.LBB0_1167:
	v_cvt_f32_i32_e32 v9, v9
	v_cvt_f32_i32_e32 v8, v8
	v_cvt_f32_i32_e32 v27, v13
	v_cvt_f32_i32_e32 v26, v12
	v_cvt_f32_i32_e32 v11, v11
	v_cvt_f32_i32_e32 v10, v10
	v_cvt_f32_i32_e32 v15, v15
	v_cvt_f32_i32_e32 v14, v14
	v_pk_mul_f32 v[8:9], v[158:159], v[8:9]
	v_mov_b32_e32 v12, v158
	v_mov_b32_e32 v13, v158
	v_pk_mul_f32 v[26:27], v[158:159], v[26:27]
	v_pk_mul_f32 v[28:29], v[8:9], v[16:17]
	v_pk_mul_f32 v[8:9], v[8:9], v[20:21]
	v_pk_mul_f32 v[10:11], v[12:13], v[10:11]
	v_pk_fma_f32 v[28:29], v[26:27], v[20:21], v[28:29] neg_lo:[0,0,1] neg_hi:[0,0,1]
	v_pk_fma_f32 v[26:27], v[26:27], v[16:17], v[8:9]
	v_lshl_add_u64 v[8:9], s[28:29], 0, v[24:25]
	v_pk_mul_f32 v[30:31], v[12:13], v[14:15]
	v_pk_mul_f32 v[14:15], v[10:11], v[18:19]
	v_pk_mul_f32 v[10:11], v[10:11], v[22:23]
	v_lshlrev_b64 v[34:35], 8, v[8:9]
	v_pk_fma_f32 v[14:15], v[30:31], v[22:23], v[14:15] neg_lo:[0,0,1] neg_hi:[0,0,1]
	v_pk_fma_f32 v[10:11], v[30:31], v[18:19], v[10:11]
	v_lshl_add_u64 v[34:35], v[148:149], 0, v[34:35]
	s_and_b64 vcc, exec, s[6:7]
	v_cvt_pk_bf16_f32 v30, v28, v29
	v_cvt_pk_bf16_f32 v31, v14, v15
	v_cvt_pk_bf16_f32 v32, v26, v27
	v_cvt_pk_bf16_f32 v33, v10, v11
	global_store_dwordx4 v[34:35], v[30:33], off
	s_cbranch_vccnz .LBB0_1171
	v_mul_f32_e32 v29, v29, v29
	v_mul_f32_e32 v15, v15, v15
	v_fmac_f32_e32 v29, v28, v28
	v_fmac_f32_e32 v15, v14, v14
	v_add_f32_e32 v14, v29, v15
	v_mul_f32_e32 v15, v27, v27
	v_mul_f32_e32 v11, v11, v11
	v_fmac_f32_e32 v15, v26, v26
	v_fmac_f32_e32 v11, v10, v10
	v_add_f32_e32 v10, v15, v11
	v_add_f32_e32 v10, v14, v10
	v_and_b32_e32 v14, 64, v171
	v_xor_b32_e32 v11, 16, v171
	v_add_u32_e32 v14, 64, v14
	v_cmp_lt_i32_e32 vcc, v11, v14
	s_nop 1
	v_cndmask_b32_e32 v11, v171, v11, vcc
	v_lshlrev_b32_e32 v11, 2, v11
	v_mov_b32_e32 v11, v10
	s_nop 1
	v_permlane16_swap_b32_e32 v10, v11
	s_waitcnt lgkmcnt(0)
	v_add_f32_e32 v10, v10, v11
	v_xor_b32_e32 v11, 32, v171
	v_cmp_lt_i32_e32 vcc, v11, v14
	s_nop 1
	v_cndmask_b32_e32 v11, v171, v11, vcc
	v_lshlrev_b32_e32 v11, 2, v11
	v_mov_b32_e32 v11, v10
	s_nop 1
	v_permlane32_swap_b32_e32 v10, v11
	s_and_saveexec_b64 s[8:9], s[2:3]
	s_cbranch_execz .LBB0_1170
	v_lshl_add_u64 v[8:9], v[8:9], 4, s[16:17]
	s_waitcnt lgkmcnt(0)
	v_add_f32_e32 v10, v10, v11
	global_store_dword v[8:9], v10, off

; __device__ __forceinline__ void ln3_router_phase(const Params& P, LAS unsigned char* lds, const int tid) {
;     ...
;     for (int c = blockIdx.x; c < NTOK / 64; c += gridDim.x) {
;         int cnt[8];
; #pragma unroll
;         for (int e = 0; e < 8; ++e) cnt[e] = 0;
; #pragma unroll 1
;         for (int i = 0; i < 8; ++i) { const int m = c * 64 + wave * 8 + i; asm volatile("" ::: "memory");
;             const u32x2* yr = (const u32x2*)(Y + (size_t)m * DM) + lane; f32x4 v[8];
.LBB0_4580:
	v_mov_b32_e32 v34, v84
	v_mov_b32_e32 v4, 0
	v_mov_b32_e32 v5, 0
	v_mov_b32_e32 v6, 0
	v_mov_b32_e32 v7, 0
	v_mov_b32_e32 v0, 0
	v_mov_b32_e32 v1, 0
	v_mov_b32_e32 v2, 0
	v_mov_b32_e32 v3, 0
	s_mov_b32 s49, 0
	s_mov_b64 s[94:95], 0x1000
	v_mov_b32_e32 v186, v85
	v_ashrrev_i32_e32 v187, 31, v85
	v_lshlrev_b64 v[186:187], 12, v[186:187]
	v_lshl_add_u64 v[186:187], v[10:11], 0, v[186:187]
	global_load_dwordx2 v[168:169], v[186:187], off offset:1536
	global_load_dwordx2 v[170:171], v[186:187], off offset:2048
	global_load_dwordx2 v[172:173], v[186:187], off offset:3072
	global_load_dwordx2 v[174:175], v[186:187], off offset:3584
	global_load_dwordx2 v[176:177], v[186:187], off
	global_load_dwordx2 v[178:179], v[186:187], off offset:512
	global_load_dwordx2 v[180:181], v[186:187], off offset:1024
	global_load_dwordx2 v[182:183], v[186:187], off offset:2560
	global_load_dword v188, v[10:11], off
	global_load_dword v188, v[10:11], off
	global_load_dword v188, v[10:11], off
	s_branch .LBB0_4582

; __device__ __forceinline__ void ln_norm2(f32x4 (&v)[8], const float* g, const float* b, int lane, float& mean_o, float& rstd_o) {
;     float s = 0.f;
; #pragma unroll
;     for (int j = 0; j < 8; ++j) s += (v[j][0] + v[j][1]) + (v[j][2] + v[j][3]);
;     const float mean = wave_sum(s) * (1.f / DM); float s2 = 0.f;
; #pragma unroll
;     for (int j = 0; j < 8; ++j) { v[j] = v[j] - mean; s2 += (v[j][0] * v[j][0] + v[j][1] * v[j][1]) + (v[j][2] * v[j][2] + v[j][3] * v[j][3]); }
; __device__ __forceinline__ f32x4 bf4x(const u32x2 a) { return (f32x4){__uint_as_float(a.x << 16), __uint_as_float(a.x & 0xffff0000u), __uint_as_float(a.y << 16), __uint_as_float(a.y & 0xffff0000u)}; }
; __device__ __forceinline__ void ln3_router_phase(const Params& P, LAS unsigned char* lds, const int tid) {
;     ...
;         for (int i = 0; i < 8; ++i) { const int m = c * 64 + wave * 8 + i; asm volatile("" ::: "memory");
;             const u32x2* yr = (const u32x2*)(Y + (size_t)m * DM) + lane; f32x4 v[8];
; #pragma unroll
;             for (int j = 0; j < 8; ++j) v[j] = bf4x(yr[64 * j]);
;             float mu3, rs3; ln_norm2(v, P.in[19], P.in[20], lane, mu3, rs3); ln_store(v, nullptr, H3B, (size_t)m, lane, -ASC_XI8);
.LBB0_4582:
	v_add_u32_e32 v68, s49, v85
	v_ashrrev_i32_e32 v69, 31, v68
	v_lshlrev_b64 v[36:37], 12, v[68:69]
	v_lshl_add_u64 v[36:37], v[10:11], 0, v[36:37]
	v_mov_b32_e32 v184, v36
	v_mov_b32_e32 v185, v37
	s_waitcnt vmcnt(3)
	v_mov_b32_e32 v38, v168
	v_mov_b32_e32 v39, v169
	v_mov_b32_e32 v40, v170
	v_mov_b32_e32 v41, v171
	v_mov_b32_e32 v44, v172
	v_mov_b32_e32 v45, v173
	v_mov_b32_e32 v52, v174
	v_mov_b32_e32 v53, v175
	v_mov_b32_e32 v56, v176
	v_mov_b32_e32 v57, v177
	v_mov_b32_e32 v62, v178
	v_mov_b32_e32 v63, v179
	v_mov_b32_e32 v64, v180
	v_mov_b32_e32 v65, v181
	v_mov_b32_e32 v66, v182
	v_mov_b32_e32 v67, v183
	v_cmp_lt_i32_e32 vcc, v88, v87
	v_lshlrev_b64 v[68:69], 11, v[68:69]
	v_lshl_add_u64 v[68:69], v[12:13], 0, v[68:69]
	v_cndmask_b32_e32 v35, v86, v88, vcc
	v_lshlrev_b32_e32 v100, 2, v35
	v_cmp_lt_i32_e32 vcc, v89, v87
	v_lshlrev_b32_e32 v48, 16, v38
	v_lshlrev_b32_e32 v46, 16, v40
	v_and_b32_e32 v76, 0xffff0000, v40
	v_lshlrev_b32_e32 v36, 16, v44
	v_lshlrev_b32_e32 v59, 16, v56
	v_lshlrev_b32_e32 v58, 16, v62
	v_and_b32_e32 v61, 0xffff0000, v56
	v_and_b32_e32 v60, 0xffff0000, v62
	v_lshlrev_b32_e32 v55, 16, v57
	v_lshlrev_b32_e32 v54, 16, v63
	v_and_b32_e32 v57, 0xffff0000, v57
	v_and_b32_e32 v56, 0xffff0000, v63
	v_and_b32_e32 v37, 0xffff0000, v44
	v_lshlrev_b32_e32 v44, 16, v52
	v_and_b32_e32 v72, 0xffff0000, v52
	v_lshlrev_b32_e32 v40, 16, v53
	v_and_b32_e32 v70, 0xffff0000, v53
	v_lshlrev_b32_e32 v53, 16, v65
	v_lshlrev_b32_e32 v52, 16, v64
	v_and_b32_e32 v63, 0xffff0000, v65
	v_and_b32_e32 v62, 0xffff0000, v64
	v_lshlrev_b32_e32 v79, 16, v67
	v_lshlrev_b32_e32 v78, 16, v66
	v_and_b32_e32 v65, 0xffff0000, v67
	v_and_b32_e32 v64, 0xffff0000, v66
	v_pk_add_f32 v[66:67], v[58:59], v[60:61]
	v_pk_add_f32 v[80:81], v[54:55], v[56:57]
	v_pk_add_f32 v[102:103], v[52:53], v[62:63]
	v_pk_add_f32 v[66:67], v[66:67], v[80:81]
	v_and_b32_e32 v49, 0xffff0000, v38
	v_lshlrev_b32_e32 v50, 16, v39
	v_and_b32_e32 v51, 0xffff0000, v39
	v_pk_add_f32 v[80:81], v[102:103], v[102:103] op_sel_hi:[0,1]
	v_add_f32_e32 v35, 0, v67
	v_lshlrev_b32_e32 v42, 16, v41
	v_and_b32_e32 v74, 0xffff0000, v41
	v_add_f32_e32 v47, v48, v49
	v_add_f32_e32 v77, v50, v51
	v_mov_b32_e32 v43, v81
	v_add_f32_e32 v75, v66, v35
	v_pk_add_f32 v[102:103], v[46:47], v[76:77]
	v_pk_add_f32 v[66:67], v[42:43], v[74:75]
	v_pk_add_f32 v[104:105], v[78:79], v[64:65]
	v_pk_add_f32 v[66:67], v[102:103], v[66:67]
	v_lshlrev_b32_e32 v38, 16, v45
	v_and_b32_e32 v39, 0xffff0000, v45
	v_pk_add_f32 v[104:105], v[104:105], v[104:105] op_sel_hi:[0,1]
	v_pk_add_f32 v[66:67], v[66:67], v[66:67] op_sel_hi:[0,1]
	v_add_f32_e32 v45, v36, v37
	v_add_f32_e32 v73, v38, v39
	v_mov_b32_e32 v41, v105
	v_mov_b32_e32 v71, v67
	v_pk_add_f32 v[106:107], v[44:45], v[72:73]
	v_pk_add_f32 v[66:67], v[40:41], v[70:71]
	v_cndmask_b32_e32 v43, v86, v89, vcc
	v_pk_add_f32 v[66:67], v[106:107], v[66:67]
	v_lshlrev_b32_e32 v71, 2, v43
	v_add_f32_e32 v35, v66, v67
	s_nop 1
	v_mov_b32_dpp v41, v35 quad_perm:[1,0,3,2] row_mask:0xf bank_mask:0xf
	v_cmp_lt_i32_e32 vcc, v90, v87
	s_waitcnt lgkmcnt(0)
	v_add_f32_e32 v35, v35, v41
	s_nop 1
	v_mov_b32_dpp v41, v35 quad_perm:[2,3,0,1] row_mask:0xf bank_mask:0xf
	v_cndmask_b32_e32 v43, v86, v90, vcc
	v_lshlrev_b32_e32 v73, 2, v43
	v_cmp_lt_i32_e32 vcc, v91, v87
	s_waitcnt lgkmcnt(0)
	v_add_f32_e32 v35, v35, v41
	s_nop 1
	v_mov_b32_dpp v41, v35 row_half_mirror row_mask:0xf bank_mask:0xf
	v_cndmask_b32_e32 v43, v86, v91, vcc
	v_lshlrev_b32_e32 v75, 2, v43
	v_cmp_lt_i32_e32 vcc, v92, v87
	s_waitcnt lgkmcnt(0)
	v_add_f32_e32 v35, v35, v41
	s_nop 1
	v_mov_b32_dpp v41, v35 row_mirror row_mask:0xf bank_mask:0xf
	v_cndmask_b32_e32 v43, v86, v92, vcc
	v_lshlrev_b32_e32 v77, 2, v43
	v_cmp_lt_i32_e32 vcc, v93, v87
	s_waitcnt lgkmcnt(0)
	v_add_f32_e32 v35, v35, v41
	v_mov_b32_e32 v41, v35
	s_nop 1
	v_permlane16_swap_b32_e32 v35, v41
	v_cndmask_b32_e32 v43, v86, v93, vcc
	v_lshlrev_b32_e32 v101, 2, v43
	s_waitcnt lgkmcnt(0)
	v_add_f32_e32 v35, v35, v41
	v_mov_b32_e32 v41, v35
	s_nop 1
	v_permlane32_swap_b32_e32 v35, v41
	s_waitcnt lgkmcnt(0)
	v_add_f32_e32 v102, v35, v41
	v_fmac_f32_e32 v57, 0xba000000, v102
	v_fmac_f32_e32 v61, 0xba000000, v102
	v_fmac_f32_e32 v56, 0xba000000, v102
	v_fmac_f32_e32 v60, 0xba000000, v102
	v_fmac_f32_e32 v55, 0xba000000, v102
	v_fmac_f32_e32 v59, 0xba000000, v102
	v_fmac_f32_e32 v54, 0xba000000, v102
	v_fmac_f32_e32 v58, 0xba000000, v102
	v_fmac_f32_e32 v62, 0xba000000, v102
	v_fmac_f32_e32 v63, 0xba000000, v102
	v_fmac_f32_e32 v53, 0xba000000, v102
	v_mov_b32_e32 v104, v61
	v_mov_b32_e32 v105, v60
	v_mov_b32_e32 v108, v57
	v_mov_b32_e32 v109, v56
	v_mov_b32_e32 v66, v59
	v_mov_b32_e32 v67, v58
	v_mov_b32_e32 v106, v55
	v_mov_b32_e32 v107, v54
	v_mov_b32_e32 v80, v53
	v_mov_b32_e32 v81, v63
	v_mov_b32_e32 v53, v62
	v_pk_mul_f32 v[62:63], v[104:105], v[104:105]
	v_pk_mul_f32 v[104:105], v[108:109], v[108:109]
	v_pk_fma_f32 v[62:63], v[66:67], v[66:67], v[62:63]
	v_pk_fma_f32 v[66:67], v[106:107], v[106:107], v[104:105]
	v_fmac_f32_e32 v52, 0xba000000, v102
	v_pk_add_f32 v[62:63], v[62:63], v[66:67]
	v_fmac_f32_e32 v48, 0xba000000, v102
	v_pk_mul_f32 v[108:109], v[80:81], v[80:81]
	v_pk_mul_f32 v[110:111], v[52:53], v[52:53]
	v_pk_add_f32 v[62:63], v[62:63], v[62:63] op_sel_hi:[0,1]
	v_fmac_f32_e32 v49, 0xba000000, v102
	v_fmac_f32_e32 v50, 0xba000000, v102
	v_pk_mov_b32 v[104:105], v[110:111], v[108:109] op_sel:[1,0]
	v_mov_b32_e32 v111, v109
	v_mul_f32_e32 v62, v48, v48
	v_fmac_f32_e32 v51, 0xba000000, v102
	v_pk_add_f32 v[66:67], v[104:105], v[110:111]
	v_pk_fma_f32 v[104:105], v[48:49], v[48:49], v[62:63] op_sel_hi:[1,1,0]
	v_mul_f32_e32 v62, v50, v50
; __device__ __forceinline__ void ln_norm2(f32x4 (&v)[8], const float* g, const float* b, int lane, float& mean_o, float& rstd_o) {
;     float s = 0.f;
; #pragma unroll
;     for (int j = 0; j < 8; ++j) s += (v[j][0] + v[j][1]) + (v[j][2] + v[j][3]);
;     const float mean = wave_sum(s) * (1.f / DM); float s2 = 0.f;
; #pragma unroll
;     for (int j = 0; j < 8; ++j) { v[j] = v[j] - mean; s2 += (v[j][0] * v[j][0] + v[j][1] * v[j][1]) + (v[j][2] * v[j][2] + v[j][3] * v[j][3]); }
;     const float rstd = 1.f / sqrtf(wave_sum(s2) * (1.f / DM) + LN_EPS);
; #pragma unroll
;     for (int j = 0; j < 8; ++j) { const f32x4 gv = *((const f32x4*)g + lane + 64 * j), bv = *((const f32x4*)b + lane + 64 * j); v[j] = v[j] * rstd * gv + bv; }
	v_pk_add_f32 v[66:67], v[66:67], v[66:67] op_sel_hi:[0,1]
	v_pk_fma_f32 v[106:107], v[50:51], v[50:51], v[62:63] op_sel_hi:[1,1,0]
	v_fmac_f32_e32 v74, 0xba000000, v102
	v_fmac_f32_e32 v42, 0xba000000, v102
	v_fmac_f32_e32 v76, 0xba000000, v102
	v_fmac_f32_e32 v46, 0xba000000, v102
	v_mul_f32_e32 v104, v46, v46
	v_mul_f32_e32 v106, v76, v76
	v_mul_f32_e32 v66, v42, v42
	v_mul_f32_e32 v62, v74, v74
	v_pk_add_f32 v[104:105], v[104:105], v[106:107]
	v_pk_add_f32 v[62:63], v[66:67], v[62:63]
	v_fmac_f32_e32 v64, 0xba000000, v102
	v_fmac_f32_e32 v65, 0xba000000, v102
	v_fmac_f32_e32 v79, 0xba000000, v102
	v_pk_add_f32 v[62:63], v[104:105], v[62:63]
	v_fmac_f32_e32 v78, 0xba000000, v102
	v_mov_b32_e32 v164, v79
	v_mov_b32_e32 v165, v65
	v_mov_b32_e32 v79, v64
	v_pk_add_f32 v[62:63], v[62:63], v[62:63] op_sel_hi:[0,1]
	v_pk_mul_f32 v[66:67], v[164:165], v[164:165]
	v_pk_mul_f32 v[64:65], v[78:79], v[78:79]
	v_fmac_f32_e32 v36, 0xba000000, v102
	v_pk_mov_b32 v[104:105], v[64:65], v[66:67] op_sel:[1,0]
	v_mov_b32_e32 v65, v67
	v_fmac_f32_e32 v37, 0xba000000, v102
	v_fmac_f32_e32 v38, 0xba000000, v102
	v_mul_f32_e32 v62, v36, v36
	v_pk_add_f32 v[64:65], v[104:105], v[64:65]
	v_fmac_f32_e32 v39, 0xba000000, v102
	v_pk_fma_f32 v[66:67], v[36:37], v[36:37], v[62:63] op_sel_hi:[1,1,0]
	v_mul_f32_e32 v62, v38, v38
	v_pk_add_f32 v[64:65], v[64:65], v[64:65] op_sel_hi:[0,1]
	v_pk_fma_f32 v[104:105], v[38:39], v[38:39], v[62:63] op_sel_hi:[1,1,0]
	v_fmac_f32_e32 v70, 0xba000000, v102
	v_fmac_f32_e32 v40, 0xba000000, v102
	v_fmac_f32_e32 v72, 0xba000000, v102
	v_fmac_f32_e32 v44, 0xba000000, v102
	v_mul_f32_e32 v66, v44, v44
	v_mul_f32_e32 v104, v72, v72
	v_mul_f32_e32 v64, v40, v40
	v_mul_f32_e32 v62, v70, v70
	v_pk_add_f32 v[66:67], v[66:67], v[104:105]
	v_pk_add_f32 v[62:63], v[64:65], v[62:63]
	v_mov_b32_e32 v166, v58
	v_pk_add_f32 v[62:63], v[66:67], v[62:63]
	v_mov_b32_e32 v58, v54
	v_add_f32_e32 v35, v62, v63
	global_load_dwordx4 v[62:65], v[14:15], off
	global_load_dwordx4 v[104:107], v[16:17], off
	global_load_dwordx4 v[108:111], v[14:15], off offset:1024
	global_load_dwordx4 v[112:115], v[16:17], off offset:1024
	global_load_dwordx4 v[116:119], v[14:15], off offset:2048
	global_load_dwordx4 v[120:123], v[16:17], off offset:2048
	global_load_dwordx4 v[124:127], v[14:15], off offset:3072
	global_load_dwordx4 v[128:131], v[16:17], off offset:3072
	global_load_dwordx4 v[132:135], v[18:19], off
	global_load_dwordx4 v[136:139], v[20:21], off
	global_load_dwordx4 v[140:143], v[22:23], off
	global_load_dwordx4 v[144:147], v[24:25], off
	global_load_dwordx4 v[148:151], v[26:27], off
	global_load_dwordx4 v[152:155], v[28:29], off
	s_nop 1
	v_mov_b32_dpp v41, v35 quad_perm:[1,0,3,2] row_mask:0xf bank_mask:0xf
	global_load_dwordx4 v[156:159], v[30:31], off
	global_load_dwordx4 v[160:163], v[32:33], off
	v_mov_b32_e32 v167, v60
	v_mov_b32_e32 v60, v59
	v_mov_b32_e32 v59, v56
	s_waitcnt lgkmcnt(0)
	v_add_f32_e32 v35, v35, v41
	s_nop 1
	v_mov_b32_dpp v41, v35 quad_perm:[2,3,0,1] row_mask:0xf bank_mask:0xf
	v_mov_b32_e32 v56, v55
	s_waitcnt lgkmcnt(0)
	v_add_f32_e32 v35, v35, v41
	s_nop 1
	v_mov_b32_dpp v41, v35 row_half_mirror row_mask:0xf bank_mask:0xf
	s_waitcnt lgkmcnt(0)
	v_add_f32_e32 v35, v35, v41
	s_nop 1
	v_mov_b32_dpp v41, v35 row_mirror row_mask:0xf bank_mask:0xf
	s_waitcnt lgkmcnt(0)
	v_add_f32_e32 v35, v35, v41
	v_mov_b32_e32 v41, v35
	s_nop 1
	v_permlane16_swap_b32_e32 v35, v41
	s_waitcnt lgkmcnt(0)
	v_add_f32_e32 v35, v35, v41
	v_mov_b32_e32 v41, v35
	s_nop 1
	v_permlane32_swap_b32_e32 v35, v41
	s_waitcnt lgkmcnt(0)
	v_add_f32_e32 v35, v35, v41
	v_fmamk_f32 v35, v35, 0x3a000000, v94
	v_rsq_f32_e32 v204, v35
	s_nop 1
	s_nop 0
	s_nop 0
	s_nop 1
	s_nop 1
	s_nop 0
	v_mov_b32_e32 v82, v204
	v_mov_b32_e32 v47, v76
	v_pk_mul_f32 v[54:55], v[60:61], v[82:83] op_sel_hi:[1,0]
	v_pk_mul_f32 v[56:57], v[56:57], v[82:83] op_sel_hi:[1,0]
	v_pk_mul_f32 v[52:53], v[52:53], v[82:83] op_sel_hi:[1,0]
	v_pk_mul_f32 v[50:51], v[50:51], v[82:83] op_sel_hi:[1,0]
	v_pk_mul_f32 v[46:47], v[46:47], v[82:83] op_sel_hi:[1,0]
	s_waitcnt vmcnt(14)
	v_pk_fma_f32 v[64:65], v[64:65], v[56:57], v[106:107]
	v_pk_fma_f32 v[66:67], v[62:63], v[54:55], v[104:105]
	v_pk_mul_f32 v[54:55], v[166:167], v[82:83] op_sel_hi:[1,0]
	v_pk_mul_f32 v[56:57], v[58:59], v[82:83] op_sel_hi:[1,0]
	s_waitcnt vmcnt(10)
	v_pk_fma_f32 v[58:59], v[116:117], v[52:53], v[120:121]
	s_waitcnt vmcnt(8)
	v_pk_fma_f32 v[52:53], v[126:127], v[50:51], v[130:131]
	s_waitcnt vmcnt(6)
	v_pk_fma_f32 v[50:51], v[132:133], v[46:47], v[136:137]
	v_pk_mul_f32 v[46:47], v[78:79], v[82:83] op_sel_hi:[1,0]
	v_pk_mul_f32 v[78:79], v[36:37], v[82:83] op_sel_hi:[1,0]
	v_pk_fma_f32 v[62:63], v[108:109], v[54:55], v[112:113]
	v_pk_mul_f32 v[54:55], v[80:81], v[82:83] op_sel_hi:[1,0]
	v_pk_mul_f32 v[36:37], v[38:39], v[82:83] op_sel_hi:[1,0]
	s_waitcnt vmcnt(2)
; __device__ __forceinline__ unsigned pack4i8(const f32x4 t) {
;     const float M = 12582912.f; const unsigned a = __float_as_uint(__builtin_amdgcn_fmed3f(t[0], -127.f, 127.f) + M), b = __float_as_uint(__builtin_amdgcn_fmed3f(t[1], -127.f, 127.f) + M),
;                    c = __float_as_uint(__builtin_amdgcn_fmed3f(t[2], -127.f, 127.f) + M), d = __float_as_uint(__builtin_amdgcn_fmed3f(t[3], -127.f, 127.f) + M);
;     return __builtin_amdgcn_perm(b, a, 0x0c0c0400u) | __builtin_amdgcn_perm(d, c, 0x04000c0cu); }
;     ...
;     if (hb && f8s != 0.f) { unsigned* o4 = (unsigned*)((unsigned char*)hb + m * DM) + lane;
; #pragma unroll
;         for (int j = 0; j < 8; ++j) { if (f8s < 0.f) { o4[64 * j] = pg8::pack4i8(v[j] * -f8s); continue; }
; __device__ __forceinline__ void ln3_router_phase(const Params& P, LAS unsigned char* lds, const int tid) {
;     ...
;             if (lane == 0) { st3[2 * m] = mu3; st3[2 * m + 1] = rs3; }
	v_pk_fma_f32 v[38:39], v[148:149], v[78:79], v[152:153]
	v_pk_mul_f32 v[78:79], v[64:65], s[38:39] op_sel_hi:[1,0]
	v_pk_mul_f32 v[80:81], v[66:67], s[38:39] op_sel_hi:[1,0]
	v_mov_b32_e32 v43, v74
	v_mov_b32_e32 v45, v72
	v_mov_b32_e32 v41, v70
	v_med3_f32 v35, v80, s39, v96
	v_med3_f32 v70, v81, s39, v96
	v_med3_f32 v72, v78, s39, v96
	v_med3_f32 v74, v79, s39, v96
	v_add_f32_e32 v35, 0x4b400000, v35
	v_add_f32_e32 v70, 0x4b400000, v70
	v_add_f32_e32 v72, 0x4b400000, v72
	v_add_f32_e32 v74, 0x4b400000, v74
	v_pk_fma_f32 v[60:61], v[110:111], v[56:57], v[114:115]
	v_perm_b32 v35, v70, v35, s42
	v_perm_b32 v70, v74, v72, s43
	v_or_b32_e32 v35, v35, v70
	v_pk_mul_f32 v[78:79], v[60:61], s[38:39] op_sel_hi:[1,0]
	v_pk_mul_f32 v[80:81], v[62:63], s[38:39] op_sel_hi:[1,0]
	global_store_dword v[68:69], v35, off
	v_med3_f32 v35, v80, s39, v96
	v_med3_f32 v70, v81, s39, v96
	v_med3_f32 v72, v78, s39, v96
	v_med3_f32 v74, v79, s39, v96
	v_add_f32_e32 v35, 0x4b400000, v35
	v_add_f32_e32 v70, 0x4b400000, v70
	v_add_f32_e32 v72, 0x4b400000, v72
	v_add_f32_e32 v74, 0x4b400000, v74
	v_pk_fma_f32 v[56:57], v[118:119], v[54:55], v[122:123]
	v_perm_b32 v35, v70, v35, s42
	v_perm_b32 v70, v74, v72, s43
	v_or_b32_e32 v35, v35, v70
	v_pk_mul_f32 v[78:79], v[56:57], s[38:39] op_sel_hi:[1,0]
	v_pk_mul_f32 v[80:81], v[58:59], s[38:39] op_sel_hi:[1,0]
	global_store_dword v[68:69], v35, off offset:256
	v_med3_f32 v35, v80, s39, v96
	v_med3_f32 v70, v81, s39, v96
	v_med3_f32 v72, v78, s39, v96
	v_med3_f32 v74, v79, s39, v96
	v_pk_mul_f32 v[48:49], v[48:49], v[82:83] op_sel_hi:[1,0]
	v_add_f32_e32 v35, 0x4b400000, v35
	v_add_f32_e32 v70, 0x4b400000, v70
	v_add_f32_e32 v72, 0x4b400000, v72
	v_add_f32_e32 v74, 0x4b400000, v74
	v_pk_fma_f32 v[54:55], v[124:125], v[48:49], v[128:129]
	v_perm_b32 v35, v70, v35, s42
	v_perm_b32 v70, v74, v72, s43
	v_or_b32_e32 v35, v35, v70
	v_pk_mul_f32 v[78:79], v[52:53], s[38:39] op_sel_hi:[1,0]
	v_pk_mul_f32 v[80:81], v[54:55], s[38:39] op_sel_hi:[1,0]
	global_store_dword v[68:69], v35, off offset:512
	v_med3_f32 v35, v80, s39, v96
	v_med3_f32 v70, v81, s39, v96
	v_med3_f32 v72, v78, s39, v96
	v_med3_f32 v74, v79, s39, v96
	v_pk_mul_f32 v[42:43], v[42:43], v[82:83] op_sel_hi:[1,0]
	v_add_f32_e32 v35, 0x4b400000, v35
	v_add_f32_e32 v70, 0x4b400000, v70
	v_add_f32_e32 v72, 0x4b400000, v72
	v_add_f32_e32 v74, 0x4b400000, v74
	v_pk_fma_f32 v[48:49], v[134:135], v[42:43], v[138:139]
	v_perm_b32 v35, v70, v35, s42
	v_perm_b32 v70, v74, v72, s43
	v_or_b32_e32 v35, v35, v70
	v_pk_mul_f32 v[78:79], v[48:49], s[38:39] op_sel_hi:[1,0]
	v_pk_mul_f32 v[80:81], v[50:51], s[38:39] op_sel_hi:[1,0]
	global_store_dword v[68:69], v35, off offset:768
	v_med3_f32 v35, v80, s39, v96
	v_med3_f32 v70, v81, s39, v96
	v_med3_f32 v72, v78, s39, v96
	v_med3_f32 v74, v79, s39, v96
	v_pk_mul_f32 v[42:43], v[164:165], v[82:83] op_sel_hi:[1,0]
	v_add_f32_e32 v35, 0x4b400000, v35
	v_add_f32_e32 v70, 0x4b400000, v70
	v_add_f32_e32 v72, 0x4b400000, v72
	v_add_f32_e32 v74, 0x4b400000, v74
	v_pk_fma_f32 v[42:43], v[142:143], v[42:43], v[146:147]
	v_pk_fma_f32 v[46:47], v[140:141], v[46:47], v[144:145]
	v_perm_b32 v35, v70, v35, s42
	v_perm_b32 v70, v74, v72, s43
	v_or_b32_e32 v35, v35, v70
	v_pk_mul_f32 v[78:79], v[42:43], s[38:39] op_sel_hi:[1,0]
	v_pk_mul_f32 v[80:81], v[46:47], s[38:39] op_sel_hi:[1,0]
	global_store_dword v[68:69], v35, off offset:1024
	v_med3_f32 v35, v80, s39, v96
	v_med3_f32 v70, v81, s39, v96
	v_med3_f32 v72, v78, s39, v96
	v_med3_f32 v74, v79, s39, v96
	v_add_f32_e32 v35, 0x4b400000, v35
	v_add_f32_e32 v70, 0x4b400000, v70
	v_add_f32_e32 v72, 0x4b400000, v72
	v_add_f32_e32 v74, 0x4b400000, v74
	v_pk_fma_f32 v[36:37], v[150:151], v[36:37], v[154:155]
	v_perm_b32 v35, v70, v35, s42
	v_perm_b32 v70, v74, v72, s43
	v_or_b32_e32 v35, v35, v70
	v_pk_mul_f32 v[78:79], v[36:37], s[38:39] op_sel_hi:[1,0]
	v_pk_mul_f32 v[80:81], v[38:39], s[38:39] op_sel_hi:[1,0]
	global_store_dword v[68:69], v35, off offset:1280
	v_med3_f32 v35, v80, s39, v96
	v_med3_f32 v70, v81, s39, v96
	v_med3_f32 v72, v78, s39, v96
	v_med3_f32 v74, v79, s39, v96
	v_pk_mul_f32 v[44:45], v[44:45], v[82:83] op_sel_hi:[1,0]
	v_pk_mul_f32 v[40:41], v[40:41], v[82:83] op_sel_hi:[1,0]
	v_add_f32_e32 v35, 0x4b400000, v35
	v_add_f32_e32 v70, 0x4b400000, v70
	v_add_f32_e32 v72, 0x4b400000, v72
	v_add_f32_e32 v74, 0x4b400000, v74
	s_waitcnt vmcnt(6)
	v_pk_fma_f32 v[40:41], v[158:159], v[40:41], v[162:163]
	v_pk_fma_f32 v[44:45], v[156:157], v[44:45], v[160:161]
	v_perm_b32 v35, v70, v35, s42
	v_perm_b32 v70, v74, v72, s43
	v_or_b32_e32 v35, v35, v70
	v_pk_mul_f32 v[78:79], v[40:41], s[38:39] op_sel_hi:[1,0]
	v_pk_mul_f32 v[80:81], v[44:45], s[38:39] op_sel_hi:[1,0]
	global_store_dword v[68:69], v35, off offset:1536
	v_med3_f32 v35, v80, s39, v96
	v_med3_f32 v70, v81, s39, v96
	v_med3_f32 v72, v78, s39, v96
	v_med3_f32 v74, v79, s39, v96
	v_add_f32_e32 v35, 0x4b400000, v35
	v_add_f32_e32 v70, 0x4b400000, v70
	v_add_f32_e32 v72, 0x4b400000, v72
	v_add_f32_e32 v74, 0x4b400000, v74
	v_perm_b32 v35, v70, v35, s42
	v_perm_b32 v70, v74, v72, s43
	v_or_b32_e32 v35, v35, v70
	global_store_dword v[68:69], v35, off offset:1792
	v_ashrrev_i32_e32 v35, 31, v34
	s_and_saveexec_b64 s[6:7], s[2:3]
	s_cbranch_execz .LBB0_4584
	v_mul_f32_e32 v68, 0x3a000000, v102
	v_lshl_add_u64 v[78:79], v[34:35], 2, s[28:29]
	v_mov_b32_e32 v69, v82
	global_store_dwordx2 v[78:79], v[68:69], off
; #define LAS __attribute__((address_space(3)))
; __device__ __forceinline__ void ln3_router_phase(const Params& P, LAS unsigned char* lds, const int tid) {
;     ...
;         for (int i = 0; i < 8; ++i) { const int m = c * 64 + wave * 8 + i; asm volatile("" ::: "memory");
;     ...
;             float l[8];
; #pragma unroll
;             for (int e = 0; e < 8; ++e) { float s = 0.f;
; #pragma unroll
;                 for (int j = 0; j < 8; ++j) { const f32x4 w = *(const LAS f32x4*)(wr + e * 2048 + 256 * j + 4 * lane); s = fmaf(v[j][0], w[0], s); s = fmaf(v[j][1], w[1], s); s = fmaf(v[j][2], w[2], s); s = fmaf(v[j][3], w[3], s); }
;                 l[e] = wave_sum(s); }
.LBB0_4584:
	s_or_b64 exec, exec, s[6:7]
	v_lshl_add_u64 v[186:187], v[184:185], 0, s[94:95]
	global_load_dwordx2 v[168:169], v[186:187], off offset:1536
	global_load_dwordx2 v[170:171], v[186:187], off offset:2048
	global_load_dwordx2 v[172:173], v[186:187], off offset:3072
	global_load_dwordx2 v[174:175], v[186:187], off offset:3584
	global_load_dwordx2 v[176:177], v[186:187], off
	global_load_dwordx2 v[178:179], v[186:187], off offset:512
	global_load_dwordx2 v[180:181], v[186:187], off offset:1024
	global_load_dwordx2 v[182:183], v[186:187], off offset:2560
	ds_read_b128 v[78:81], v9
	ds_read_b128 v[102:105], v9 offset:1024
	ds_read_b128 v[106:109], v9 offset:2048
	ds_read_b128 v[110:113], v9 offset:3072
	ds_read_b128 v[114:117], v9 offset:8192
	ds_read_b128 v[118:121], v9 offset:4096
	ds_read_b128 v[122:125], v9 offset:5120
	ds_read_b128 v[126:129], v9 offset:6144
	ds_read_b128 v[130:133], v9 offset:7168
	ds_read_b128 v[134:137], v9 offset:9216
	s_waitcnt lgkmcnt(5)
	v_mov_b32_e32 v68, v114
	v_mov_b32_e32 v69, v78
	v_pk_fma_f32 v[68:69], v[66:67], v[68:69], 0 op_sel_hi:[0,1,0]
	v_mov_b32_e32 v78, v115
	v_pk_fma_f32 v[68:69], v[66:67], v[78:79], v[68:69] op_sel:[1,0,0]
	v_mov_b32_e32 v78, v116
	v_mov_b32_e32 v79, v80
	v_pk_fma_f32 v[68:69], v[64:65], v[78:79], v[68:69] op_sel_hi:[0,1,1]
	v_mov_b32_e32 v70, v65
	v_mov_b32_e32 v80, v117
	v_pk_fma_f32 v[68:69], v[70:71], v[80:81], v[68:69] op_sel_hi:[0,1,1]
	ds_read_b128 v[78:81], v9 offset:10240
	ds_read_b128 v[114:117], v9 offset:11264
	s_waitcnt lgkmcnt(2)
	v_mov_b32_e32 v138, v134
	v_mov_b32_e32 v139, v102
	v_pk_fma_f32 v[68:69], v[62:63], v[138:139], v[68:69] op_sel_hi:[0,1,1]
	v_mov_b32_e32 v102, v135
	v_pk_fma_f32 v[68:69], v[62:63], v[102:103], v[68:69] op_sel:[1,0,0]
	v_mov_b32_e32 v102, v136
	v_mov_b32_e32 v103, v104
	v_pk_fma_f32 v[68:69], v[60:61], v[102:103], v[68:69] op_sel_hi:[0,1,1]
	v_mov_b32_e32 v70, v61
	v_mov_b32_e32 v104, v137
	v_pk_fma_f32 v[68:69], v[70:71], v[104:105], v[68:69] op_sel_hi:[0,1,1]
	s_waitcnt lgkmcnt(1)
	v_mov_b32_e32 v102, v78
	v_mov_b32_e32 v103, v106
	v_pk_fma_f32 v[68:69], v[58:59], v[102:103], v[68:69] op_sel_hi:[0,1,1]
	v_mov_b32_e32 v106, v79
	v_pk_fma_f32 v[68:69], v[58:59], v[106:107], v[68:69] op_sel:[1,0,0]
	v_mov_b32_e32 v78, v80
	v_mov_b32_e32 v79, v108
	v_pk_fma_f32 v[68:69], v[56:57], v[78:79], v[68:69] op_sel_hi:[0,1,1]
	v_mov_b32_e32 v70, v57
	v_mov_b32_e32 v108, v81
	v_pk_fma_f32 v[68:69], v[70:71], v[108:109], v[68:69] op_sel_hi:[0,1,1]
	s_waitcnt lgkmcnt(0)
	v_mov_b32_e32 v78, v114
	v_mov_b32_e32 v79, v110
	v_pk_fma_f32 v[68:69], v[54:55], v[78:79], v[68:69] op_sel_hi:[0,1,1]
	v_mov_b32_e32 v110, v115
	v_pk_fma_f32 v[68:69], v[54:55], v[110:111], v[68:69] op_sel:[1,0,0]
	v_mov_b32_e32 v78, v116
	v_mov_b32_e32 v79, v112
	v_pk_fma_f32 v[68:69], v[52:53], v[78:79], v[68:69] op_sel_hi:[0,1,1]
	ds_read_b128 v[78:81], v9 offset:12288
	ds_read_b128 v[102:105], v9 offset:13312
	ds_read_b128 v[106:109], v9 offset:14336
	v_mov_b32_e32 v70, v53
	v_mov_b32_e32 v112, v117
	v_pk_fma_f32 v[68:69], v[70:71], v[112:113], v[68:69] op_sel_hi:[0,1,1]
	s_waitcnt lgkmcnt(2)
	v_mov_b32_e32 v110, v78
	v_mov_b32_e32 v111, v118
	v_pk_fma_f32 v[68:69], v[50:51], v[110:111], v[68:69] op_sel_hi:[0,1,1]
	v_mov_b32_e32 v118, v79
	v_pk_fma_f32 v[68:69], v[50:51], v[118:119], v[68:69] op_sel:[1,0,0]
	v_mov_b32_e32 v78, v80
	v_mov_b32_e32 v79, v120
	v_pk_fma_f32 v[68:69], v[48:49], v[78:79], v[68:69] op_sel_hi:[0,1,1]
	v_mov_b32_e32 v70, v49
	v_mov_b32_e32 v120, v81
	v_pk_fma_f32 v[68:69], v[70:71], v[120:121], v[68:69] op_sel_hi:[0,1,1]
	s_waitcnt lgkmcnt(1)
	v_mov_b32_e32 v78, v102
	v_mov_b32_e32 v79, v122
	v_pk_fma_f32 v[68:69], v[46:47], v[78:79], v[68:69] op_sel_hi:[0,1,1]
	v_mov_b32_e32 v122, v103
	v_pk_fma_f32 v[68:69], v[46:47], v[122:123], v[68:69] op_sel:[1,0,0]
	v_mov_b32_e32 v78, v104
	v_mov_b32_e32 v79, v124
	v_pk_fma_f32 v[68:69], v[42:43], v[78:79], v[68:69] op_sel_hi:[0,1,1]
	v_mov_b32_e32 v70, v43
	v_mov_b32_e32 v124, v105
	ds_read_b128 v[78:81], v9 offset:15360
	v_pk_fma_f32 v[68:69], v[70:71], v[124:125], v[68:69] op_sel_hi:[0,1,1]
	s_waitcnt lgkmcnt(1)
	v_mov_b32_e32 v102, v106
	v_mov_b32_e32 v103, v126
	v_pk_fma_f32 v[68:69], v[38:39], v[102:103], v[68:69] op_sel_hi:[0,1,1]
	v_mov_b32_e32 v126, v107
	v_pk_fma_f32 v[68:69], v[38:39], v[126:127], v[68:69] op_sel:[1,0,0]
	v_mov_b32_e32 v102, v108
	v_mov_b32_e32 v103, v128
	v_pk_fma_f32 v[68:69], v[36:37], v[102:103], v[68:69] op_sel_hi:[0,1,1]
	v_mov_b32_e32 v70, v37
	v_mov_b32_e32 v128, v109
	v_pk_fma_f32 v[68:69], v[70:71], v[128:129], v[68:69] op_sel_hi:[0,1,1]
	s_waitcnt lgkmcnt(0)
	v_mov_b32_e32 v102, v78
	v_mov_b32_e32 v103, v130
	v_pk_fma_f32 v[68:69], v[44:45], v[102:103], v[68:69] op_sel_hi:[0,1,1]
	v_mov_b32_e32 v130, v79
	v_pk_fma_f32 v[68:69], v[44:45], v[130:131], v[68:69] op_sel:[1,0,0]
	v_mov_b32_e32 v78, v80
	v_mov_b32_e32 v79, v132
	v_pk_fma_f32 v[68:69], v[40:41], v[78:79], v[68:69] op_sel_hi:[0,1,1]
	v_mov_b32_e32 v70, v41
	v_mov_b32_e32 v132, v81
	v_pk_fma_f32 v[68:69], v[70:71], v[132:133], v[68:69] op_sel_hi:[0,1,1]
	s_nop 1
	v_mov_b32_dpp v79, v69 quad_perm:[1,0,3,2] row_mask:0xf bank_mask:0xf
	s_nop 1
	v_mov_b32_dpp v78, v68 quad_perm:[1,0,3,2] row_mask:0xf bank_mask:0xf
	s_waitcnt lgkmcnt(0)
	v_pk_add_f32 v[68:69], v[68:69], v[78:79]
	s_nop 1
	v_mov_b32_dpp v103, v69 quad_perm:[2,3,0,1] row_mask:0xf bank_mask:0xf
	s_nop 1
	v_mov_b32_dpp v102, v68 quad_perm:[2,3,0,1] row_mask:0xf bank_mask:0xf
	ds_read_b128 v[78:81], v9 offset:16384
	s_waitcnt lgkmcnt(0)
	v_pk_add_f32 v[68:69], v[68:69], v[102:103]
	ds_read_b128 v[102:105], v9 offset:17408
	s_waitcnt lgkmcnt(1)
; #define LAS __attribute__((address_space(3)))
; __device__ __forceinline__ void ln3_router_phase(const Params& P, LAS unsigned char* lds, const int tid) {
;     ...
; #pragma unroll
;             for (int e = 0; e < 8; ++e) { float s = 0.f;
; #pragma unroll
;                 for (int j = 0; j < 8; ++j) { const f32x4 w = *(const LAS f32x4*)(wr + e * 2048 + 256 * j + 4 * lane); s = fmaf(v[j][0], w[0], s); s = fmaf(v[j][1], w[1], s); s = fmaf(v[j][2], w[2], s); s = fmaf(v[j][3], w[3], s); }
;                 l[e] = wave_sum(s); }
	v_fma_f32 v70, v66, v78, 0
	v_fmac_f32_e32 v70, v67, v79
	v_fmac_f32_e32 v70, v64, v80
	v_fmac_f32_e32 v70, v65, v81
	ds_read_b128 v[78:81], v9 offset:18432
	s_waitcnt lgkmcnt(1)
	v_fmac_f32_e32 v70, v62, v102
	v_fmac_f32_e32 v70, v63, v103
	v_fmac_f32_e32 v70, v60, v104
	v_fmac_f32_e32 v70, v61, v105
	ds_read_b128 v[102:105], v9 offset:19456
	s_waitcnt lgkmcnt(1)
	v_fmac_f32_e32 v70, v58, v78
	v_fmac_f32_e32 v70, v59, v79
	v_fmac_f32_e32 v70, v56, v80
	v_fmac_f32_e32 v70, v57, v81
	ds_read_b128 v[78:81], v9 offset:20480
	s_waitcnt lgkmcnt(1)
	v_fmac_f32_e32 v70, v54, v102
	v_fmac_f32_e32 v70, v55, v103
	v_fmac_f32_e32 v70, v52, v104
	v_fmac_f32_e32 v70, v53, v105
	ds_read_b128 v[102:105], v9 offset:21504
	s_waitcnt lgkmcnt(1)
	v_fmac_f32_e32 v70, v50, v78
	v_fmac_f32_e32 v70, v51, v79
	v_fmac_f32_e32 v70, v48, v80
	v_fmac_f32_e32 v70, v49, v81
	ds_read_b128 v[78:81], v9 offset:22528
	s_waitcnt lgkmcnt(1)
	v_fmac_f32_e32 v70, v46, v102
	v_fmac_f32_e32 v70, v47, v103
	v_fmac_f32_e32 v70, v42, v104
	v_fmac_f32_e32 v70, v43, v105
	ds_read_b128 v[102:105], v9 offset:23552
	s_waitcnt lgkmcnt(1)
	v_fmac_f32_e32 v70, v38, v78
	v_fmac_f32_e32 v70, v39, v79
	v_fmac_f32_e32 v70, v36, v80
	v_fmac_f32_e32 v70, v37, v81
	s_waitcnt lgkmcnt(0)
	v_fmac_f32_e32 v70, v44, v102
	v_fmac_f32_e32 v70, v45, v103
	v_fmac_f32_e32 v70, v40, v104
	s_nop 1
	v_mov_b32_dpp v107, v69 row_half_mirror row_mask:0xf bank_mask:0xf
	s_nop 1
	v_mov_b32_dpp v106, v68 row_half_mirror row_mask:0xf bank_mask:0xf
	v_fmac_f32_e32 v70, v41, v105
	s_nop 1
	v_mov_b32_dpp v72, v70 quad_perm:[1,0,3,2] row_mask:0xf bank_mask:0xf
	s_waitcnt lgkmcnt(0)
	v_pk_add_f32 v[68:69], v[68:69], v[106:107]
	s_nop 1
	v_mov_b32_dpp v79, v69 row_mirror row_mask:0xf bank_mask:0xf
	s_nop 1
	v_mov_b32_dpp v78, v68 row_mirror row_mask:0xf bank_mask:0xf
	s_waitcnt lgkmcnt(0)
	v_add_f32_e32 v70, v70, v72
	s_nop 1
	v_mov_b32_dpp v72, v70 quad_perm:[2,3,0,1] row_mask:0xf bank_mask:0xf
	s_waitcnt lgkmcnt(0)
	v_pk_add_f32 v[68:69], v[68:69], v[78:79]
	ds_bpermute_b32 v103, v77, v69
	ds_bpermute_b32 v102, v77, v68
	s_waitcnt lgkmcnt(2)
	v_add_f32_e32 v70, v70, v72
	s_nop 1
	v_mov_b32_dpp v72, v70 row_half_mirror row_mask:0xf bank_mask:0xf
	ds_read_b128 v[78:81], v9 offset:24576
	s_waitcnt lgkmcnt(1)
	v_pk_add_f32 v[68:69], v[68:69], v[102:103]
	ds_read_b128 v[102:105], v9 offset:25600
	s_waitcnt lgkmcnt(1)
	v_add_f32_e32 v70, v70, v72
	s_waitcnt lgkmcnt(0)
	v_fma_f32 v72, v66, v78, 0
	v_fmac_f32_e32 v72, v67, v79
	v_fmac_f32_e32 v72, v64, v80
	v_fmac_f32_e32 v72, v65, v81
	ds_read_b128 v[78:81], v9 offset:26624
	s_waitcnt lgkmcnt(1)
	v_fmac_f32_e32 v72, v62, v102
	v_fmac_f32_e32 v72, v63, v103
	v_fmac_f32_e32 v72, v60, v104
	v_fmac_f32_e32 v72, v61, v105
	ds_read_b128 v[102:105], v9 offset:27648
	s_waitcnt lgkmcnt(1)
	v_fmac_f32_e32 v72, v58, v78
	v_fmac_f32_e32 v72, v59, v79
	v_fmac_f32_e32 v72, v56, v80
	v_fmac_f32_e32 v72, v57, v81
	ds_read_b128 v[78:81], v9 offset:28672
	s_waitcnt lgkmcnt(1)
	v_fmac_f32_e32 v72, v54, v102
	v_fmac_f32_e32 v72, v55, v103
	v_fmac_f32_e32 v72, v52, v104
	v_fmac_f32_e32 v72, v53, v105
	ds_read_b128 v[102:105], v9 offset:29696
	s_waitcnt lgkmcnt(1)
	v_fmac_f32_e32 v72, v50, v78
	v_fmac_f32_e32 v72, v51, v79
	v_fmac_f32_e32 v72, v48, v80
	v_fmac_f32_e32 v72, v49, v81
	ds_read_b128 v[78:81], v9 offset:30720
	s_waitcnt lgkmcnt(1)
	v_fmac_f32_e32 v72, v46, v102
	v_fmac_f32_e32 v72, v47, v103
	v_fmac_f32_e32 v72, v42, v104
	v_fmac_f32_e32 v72, v43, v105
	ds_read_b128 v[102:105], v9 offset:31744
	s_waitcnt lgkmcnt(1)
	v_fmac_f32_e32 v72, v38, v78
	v_fmac_f32_e32 v72, v39, v79
	v_fmac_f32_e32 v72, v36, v80
	v_fmac_f32_e32 v72, v37, v81
	ds_read_b128 v[78:81], v9 offset:32768
	s_waitcnt lgkmcnt(1)
	v_fmac_f32_e32 v72, v44, v102
	v_fmac_f32_e32 v72, v45, v103
	v_fmac_f32_e32 v72, v40, v104
	v_fmac_f32_e32 v72, v41, v105
	ds_read_b128 v[102:105], v9 offset:33792
	s_waitcnt lgkmcnt(1)
	v_fma_f32 v76, v66, v78, 0
	v_fmac_f32_e32 v76, v67, v79
	v_fmac_f32_e32 v76, v64, v80
	v_fmac_f32_e32 v76, v65, v81
	ds_read_b128 v[78:81], v9 offset:34816
	s_waitcnt lgkmcnt(1)
	v_fmac_f32_e32 v76, v62, v102
	v_fmac_f32_e32 v76, v63, v103
	v_fmac_f32_e32 v76, v60, v104
	v_fmac_f32_e32 v76, v61, v105
	ds_read_b128 v[102:105], v9 offset:35840
	s_waitcnt lgkmcnt(1)
	v_fmac_f32_e32 v76, v58, v78
	v_fmac_f32_e32 v76, v59, v79
	v_fmac_f32_e32 v76, v56, v80
	v_fmac_f32_e32 v76, v57, v81
	ds_read_b128 v[78:81], v9 offset:36864
	s_waitcnt lgkmcnt(1)
	v_fmac_f32_e32 v76, v54, v102
	v_fmac_f32_e32 v76, v55, v103
	v_fmac_f32_e32 v76, v52, v104
	v_fmac_f32_e32 v76, v53, v105
	ds_read_b128 v[102:105], v9 offset:37888
	s_waitcnt lgkmcnt(1)
	v_fmac_f32_e32 v76, v50, v78
	v_fmac_f32_e32 v76, v51, v79
	v_fmac_f32_e32 v76, v48, v80
	v_fmac_f32_e32 v76, v49, v81
	ds_read_b128 v[78:81], v9 offset:38912
	s_waitcnt lgkmcnt(1)
	v_fmac_f32_e32 v76, v46, v102
	v_fmac_f32_e32 v76, v47, v103
	v_fmac_f32_e32 v76, v42, v104
	v_fmac_f32_e32 v76, v43, v105
	ds_read_b128 v[102:105], v9 offset:39936
	s_waitcnt lgkmcnt(1)
	v_fmac_f32_e32 v76, v38, v78
	v_fmac_f32_e32 v76, v39, v79
	v_fmac_f32_e32 v76, v36, v80
	v_fmac_f32_e32 v76, v37, v81
	s_waitcnt lgkmcnt(0)
	v_fmac_f32_e32 v76, v44, v102
	v_fmac_f32_e32 v76, v45, v103
	v_fmac_f32_e32 v76, v40, v104
	v_fmac_f32_e32 v76, v41, v105
	s_nop 1
	v_mov_b32_dpp v78, v76 quad_perm:[1,0,3,2] row_mask:0xf bank_mask:0xf
	s_nop 1
	v_mov_b32_dpp v80, v70 row_mirror row_mask:0xf bank_mask:0xf
	ds_bpermute_b32 v79, v101, v69
	ds_read_b128 v[102:105], v9 offset:41984
	s_nop 1
	v_mov_b32_dpp v74, v72 quad_perm:[1,0,3,2] row_mask:0xf bank_mask:0xf
	s_waitcnt lgkmcnt(1)
; #define LAS __attribute__((address_space(3)))
; __device__ __forceinline__ void ln3_router_phase(const Params& P, LAS unsigned char* lds, const int tid) {
;     ...
; #pragma unroll
;             for (int e = 0; e < 8; ++e) { float s = 0.f;
; #pragma unroll
;                 for (int j = 0; j < 8; ++j) { const f32x4 w = *(const LAS f32x4*)(wr + e * 2048 + 256 * j + 4 * lane); s = fmaf(v[j][0], w[0], s); s = fmaf(v[j][1], w[1], s); s = fmaf(v[j][2], w[2], s); s = fmaf(v[j][3], w[3], s); }
;                 l[e] = wave_sum(s); }
	v_add_f32_e32 v76, v76, v78
	s_nop 1
	v_mov_b32_dpp v78, v76 quad_perm:[2,3,0,1] row_mask:0xf bank_mask:0xf
	s_waitcnt lgkmcnt(0)
	v_add_f32_e32 v70, v70, v80
	v_mov_b32_e32 v80, v70
	s_nop 1
	v_permlane16_swap_b32_e32 v70, v80
	s_waitcnt lgkmcnt(1)
	v_add_f32_e32 v72, v72, v74
	s_nop 1
	v_mov_b32_dpp v74, v72 quad_perm:[2,3,0,1] row_mask:0xf bank_mask:0xf
	s_waitcnt lgkmcnt(0)
	v_add_f32_e32 v76, v76, v78
	s_nop 1
	v_mov_b32_dpp v81, v76 row_half_mirror row_mask:0xf bank_mask:0xf
	s_waitcnt lgkmcnt(0)
	v_add_f32_e32 v70, v70, v80
	ds_bpermute_b32 v78, v101, v68
	s_waitcnt lgkmcnt(2)
	v_add_f32_e32 v72, v72, v74
	s_nop 1
	v_mov_b32_dpp v74, v72 row_half_mirror row_mask:0xf bank_mask:0xf
	s_waitcnt lgkmcnt(1)
	v_add_f32_e32 v76, v76, v81
	s_nop 1
	v_mov_b32_dpp v80, v76 row_mirror row_mask:0xf bank_mask:0xf
	v_mov_b32_e32 v81, v70
	s_nop 1
	v_permlane32_swap_b32_e32 v70, v81
	s_waitcnt lgkmcnt(0)
	v_pk_add_f32 v[68:69], v[68:69], v[78:79]
	s_waitcnt lgkmcnt(0)
	v_add_f32_e32 v72, v72, v74
	s_nop 1
	v_mov_b32_dpp v74, v72 row_mirror row_mask:0xf bank_mask:0xf
	s_waitcnt lgkmcnt(1)
	v_add_f32_e32 v76, v76, v80
	s_waitcnt lgkmcnt(0)
	v_add_f32_e32 v70, v70, v81
	ds_read_b128 v[78:81], v9 offset:40960
	ds_bpermute_b32 v82, v77, v76
	s_waitcnt lgkmcnt(2)
	v_add_f32_e32 v72, v72, v74
	ds_bpermute_b32 v74, v77, v72
	v_cmp_gt_f32_e32 vcc, v68, v69
	s_waitcnt lgkmcnt(2)
	v_fma_f32 v106, v66, v78, 0
	v_fmac_f32_e32 v106, v67, v79
	v_fmac_f32_e32 v106, v64, v80
	v_fmac_f32_e32 v106, v65, v81
	ds_read_b128 v[78:81], v9 offset:43008
	v_fmac_f32_e32 v106, v62, v102
	v_fmac_f32_e32 v106, v63, v103
	v_fmac_f32_e32 v106, v60, v104
	v_fmac_f32_e32 v106, v61, v105
	ds_read_b128 v[102:105], v9 offset:44032
	s_waitcnt lgkmcnt(1)
	v_fmac_f32_e32 v106, v58, v78
	v_fmac_f32_e32 v106, v59, v79
	v_fmac_f32_e32 v106, v56, v80
	v_fmac_f32_e32 v106, v57, v81
	ds_read_b128 v[78:81], v9 offset:45056
	s_waitcnt lgkmcnt(1)
	v_fmac_f32_e32 v106, v54, v102
	v_fmac_f32_e32 v106, v55, v103
	v_fmac_f32_e32 v106, v52, v104
	v_fmac_f32_e32 v106, v53, v105
	ds_read_b128 v[102:105], v9 offset:46080
	s_waitcnt lgkmcnt(1)
	v_fmac_f32_e32 v106, v50, v78
	v_fmac_f32_e32 v106, v51, v79
	v_fmac_f32_e32 v106, v48, v80
	v_fmac_f32_e32 v106, v49, v81
	ds_read_b128 v[78:81], v9 offset:47104
	s_waitcnt lgkmcnt(1)
	v_fmac_f32_e32 v106, v46, v102
	v_fmac_f32_e32 v106, v47, v103
	v_fmac_f32_e32 v106, v42, v104
	v_fmac_f32_e32 v106, v43, v105
	ds_read_b128 v[102:105], v9 offset:48128
	s_waitcnt lgkmcnt(1)
	v_fmac_f32_e32 v106, v38, v78
	v_fmac_f32_e32 v106, v39, v79
	v_fmac_f32_e32 v106, v36, v80
	v_fmac_f32_e32 v106, v37, v81
	ds_read_b128 v[78:81], v9 offset:49152
	s_waitcnt lgkmcnt(1)
	v_fmac_f32_e32 v106, v44, v102
	v_fmac_f32_e32 v106, v45, v103
	v_fmac_f32_e32 v106, v40, v104
	v_fmac_f32_e32 v106, v41, v105
	ds_read_b128 v[102:105], v9 offset:50176
	s_waitcnt lgkmcnt(1)
	v_fma_f32 v108, v66, v78, 0
	v_fmac_f32_e32 v108, v67, v79
	v_fmac_f32_e32 v108, v64, v80
	v_fmac_f32_e32 v108, v65, v81
	ds_read_b128 v[78:81], v9 offset:51200
	s_waitcnt lgkmcnt(1)
	v_fmac_f32_e32 v108, v62, v102
	v_fmac_f32_e32 v108, v63, v103
	v_fmac_f32_e32 v108, v60, v104
	v_fmac_f32_e32 v108, v61, v105
	ds_read_b128 v[102:105], v9 offset:52224
	s_waitcnt lgkmcnt(1)
	v_fmac_f32_e32 v108, v58, v78
	v_fmac_f32_e32 v108, v59, v79
	v_fmac_f32_e32 v108, v56, v80
	v_fmac_f32_e32 v108, v57, v81
	ds_read_b128 v[78:81], v9 offset:53248
	s_waitcnt lgkmcnt(1)
	v_fmac_f32_e32 v108, v54, v102
	v_fmac_f32_e32 v108, v55, v103
	v_fmac_f32_e32 v108, v52, v104
	v_fmac_f32_e32 v108, v53, v105
	ds_read_b128 v[102:105], v9 offset:54272
	s_waitcnt lgkmcnt(1)
	v_fmac_f32_e32 v108, v50, v78
	v_fmac_f32_e32 v108, v51, v79
	v_fmac_f32_e32 v108, v48, v80
	v_fmac_f32_e32 v108, v49, v81
	ds_read_b128 v[78:81], v9 offset:55296
	s_waitcnt lgkmcnt(1)
	v_fmac_f32_e32 v108, v46, v102
	v_fmac_f32_e32 v108, v47, v103
	v_fmac_f32_e32 v108, v42, v104
	v_fmac_f32_e32 v108, v43, v105
	ds_read_b128 v[102:105], v9 offset:56320
	s_waitcnt lgkmcnt(1)
	v_fmac_f32_e32 v108, v38, v78
	v_fmac_f32_e32 v108, v39, v79
	v_fmac_f32_e32 v108, v36, v80
	v_fmac_f32_e32 v108, v37, v81
	ds_read_b128 v[78:81], v9 offset:57344
	s_waitcnt lgkmcnt(1)
	v_fmac_f32_e32 v108, v44, v102
	v_fmac_f32_e32 v108, v45, v103
	v_fmac_f32_e32 v108, v40, v104
	v_fmac_f32_e32 v108, v41, v105
	ds_read_b128 v[102:105], v9 offset:58368
	s_waitcnt lgkmcnt(1)
	v_fma_f32 v78, v66, v78, 0
	v_fmac_f32_e32 v78, v67, v79
	v_fmac_f32_e32 v78, v64, v80
	v_fmac_f32_e32 v78, v65, v81
	ds_read_b128 v[64:67], v9 offset:59392
	s_waitcnt lgkmcnt(1)
	v_fmac_f32_e32 v78, v62, v102
	v_fmac_f32_e32 v78, v63, v103
	v_fmac_f32_e32 v78, v60, v104
	v_fmac_f32_e32 v78, v61, v105
	ds_read_b128 v[60:63], v9 offset:60416
	s_waitcnt lgkmcnt(1)
	v_fmac_f32_e32 v78, v58, v64
	v_fmac_f32_e32 v78, v59, v65
	v_fmac_f32_e32 v78, v56, v66
	v_fmac_f32_e32 v78, v57, v67
	ds_read_b128 v[56:59], v9 offset:61440
	s_waitcnt lgkmcnt(1)
	v_fmac_f32_e32 v78, v54, v60
	v_fmac_f32_e32 v78, v55, v61
	v_fmac_f32_e32 v78, v52, v62
	v_fmac_f32_e32 v78, v53, v63
	ds_read_b128 v[52:55], v9 offset:62464
	s_waitcnt lgkmcnt(1)
	v_fmac_f32_e32 v78, v50, v56
	v_fmac_f32_e32 v78, v51, v57
	v_fmac_f32_e32 v78, v48, v58
	v_fmac_f32_e32 v78, v49, v59
	ds_read_b128 v[48:51], v9 offset:63488
	s_waitcnt lgkmcnt(1)
	v_fmac_f32_e32 v78, v46, v52
	v_fmac_f32_e32 v78, v47, v53
	v_fmac_f32_e32 v78, v42, v54
	v_fmac_f32_e32 v78, v43, v55
	ds_read_b128 v[52:55], v9 offset:64512
	s_waitcnt lgkmcnt(1)
	v_fmac_f32_e32 v78, v38, v48
	v_fmac_f32_e32 v78, v39, v49
	v_fmac_f32_e32 v78, v36, v50
	v_fmac_f32_e32 v78, v37, v51
	s_waitcnt lgkmcnt(0)
; __device__ __forceinline__ void ln3_router_phase(const Params& P, LAS unsigned char* lds, const int tid) {
;     ...
;             float v1 = l[0]; int e1 = 0;
; #pragma unroll
;             for (int e = 1; e < 8; ++e) if (l[e] > v1) { v1 = l[e]; e1 = e; }
;             float v2 = -__builtin_inff(); int e2 = 0;
; #pragma unroll
;             for (int e = 0; e < 8; ++e) if (e != e1 && l[e] > v2) { v2 = l[e]; e2 = e; }
;             const float ex = expf(v2 - v1), g1 = 1.0f / (1.0f + ex), g2 = ex / (1.0f + ex);
;             if (lane == 0) { rte[2 * m] = e1; rte[2 * m + 1] = e2; rtg[2 * m] = g1; rtg[2 * m + 1] = g2; }
; #pragma unroll
;             for (int e = 0; e < 8; ++e) cnt[e] += (e1 == e) + (e2 == e);
	v_fmac_f32_e32 v78, v44, v52
	v_fmac_f32_e32 v78, v45, v53
	v_fmac_f32_e32 v78, v40, v54
	v_fmac_f32_e32 v78, v41, v55
	s_nop 1
	v_mov_b32_dpp v107, v106 quad_perm:[1,0,3,2] row_mask:0xf bank_mask:0xf
	s_nop 1
	v_mov_b32_dpp v36, v78 quad_perm:[1,0,3,2] row_mask:0xf bank_mask:0xf
	s_nop 1
	v_mov_b32_dpp v109, v108 quad_perm:[1,0,3,2] row_mask:0xf bank_mask:0xf
	v_add_f32_e32 v72, v72, v74
	v_mov_b32_e32 v74, v72
	s_nop 1
	v_permlane32_swap_b32_e32 v72, v74
	s_waitcnt lgkmcnt(0)
	v_add_f32_e32 v37, v106, v107
	s_waitcnt lgkmcnt(2)
	v_add_f32_e32 v36, v78, v36
	s_nop 1
	v_mov_b32_dpp v38, v37 quad_perm:[2,3,0,1] row_mask:0xf bank_mask:0xf
	s_waitcnt lgkmcnt(1)
	v_add_f32_e32 v39, v108, v109
	s_nop 1
	v_mov_b32_dpp v41, v36 quad_perm:[2,3,0,1] row_mask:0xf bank_mask:0xf
	s_nop 1
	v_mov_b32_dpp v40, v39 quad_perm:[2,3,0,1] row_mask:0xf bank_mask:0xf
	v_add_f32_e32 v76, v76, v82
	s_waitcnt lgkmcnt(0)
	v_add_f32_e32 v37, v37, v38
	s_nop 1
	v_mov_b32_dpp v38, v37 row_half_mirror row_mask:0xf bank_mask:0xf
	s_waitcnt lgkmcnt(1)
	v_add_f32_e32 v36, v36, v41
	s_waitcnt lgkmcnt(0)
	v_add_f32_e32 v39, v39, v40
	s_nop 1
	v_mov_b32_dpp v41, v36 row_half_mirror row_mask:0xf bank_mask:0xf
	s_nop 1
	v_mov_b32_dpp v40, v39 row_half_mirror row_mask:0xf bank_mask:0xf
	s_waitcnt lgkmcnt(0)
	v_add_f32_e32 v37, v37, v38
	s_nop 1
	v_mov_b32_dpp v38, v37 row_mirror row_mask:0xf bank_mask:0xf
	v_mov_b32_e32 v82, v76
	s_nop 1
	v_permlane32_swap_b32_e32 v76, v82
	s_waitcnt lgkmcnt(1)
	v_add_f32_e32 v36, v36, v41
	s_waitcnt lgkmcnt(0)
	v_add_f32_e32 v39, v39, v40
	s_nop 1
	v_mov_b32_dpp v41, v36 row_mirror row_mask:0xf bank_mask:0xf
	s_nop 1
	v_mov_b32_dpp v40, v39 row_mirror row_mask:0xf bank_mask:0xf
	s_waitcnt lgkmcnt(0)
	v_add_f32_e32 v37, v37, v38
	v_mov_b32_e32 v38, v37
	s_nop 1
	v_permlane16_swap_b32_e32 v37, v38
	v_add_f32_e32 v42, v72, v74
	s_waitcnt lgkmcnt(1)
	v_add_f32_e32 v36, v36, v41
	s_waitcnt lgkmcnt(0)
	v_add_f32_e32 v39, v39, v40
	v_mov_b32_e32 v41, v36
	s_nop 1
	v_permlane16_swap_b32_e32 v36, v41
	v_mov_b32_e32 v40, v39
	s_nop 1
	v_permlane16_swap_b32_e32 v39, v40
	s_waitcnt lgkmcnt(0)
	v_add_f32_e32 v37, v37, v38
	v_mov_b32_e32 v38, v37
	s_nop 1
	v_permlane32_swap_b32_e32 v37, v38
	v_add_f32_e32 v43, v76, v82
	s_waitcnt lgkmcnt(1)
	v_add_f32_e32 v36, v36, v41
	s_waitcnt lgkmcnt(0)
	v_add_f32_e32 v39, v39, v40
	v_mov_b32_e32 v41, v36
	s_nop 1
	v_permlane32_swap_b32_e32 v36, v41
	v_mov_b32_e32 v40, v39
	s_nop 1
	v_permlane32_swap_b32_e32 v39, v40
	s_waitcnt lgkmcnt(0)
	v_add_f32_e32 v37, v37, v38
	v_cmp_nlg_f32_e64 s[10:11], s44, v69
	s_waitcnt lgkmcnt(1)
	v_add_f32_e32 v38, v36, v41
	v_cndmask_b32_e32 v36, v69, v68, vcc
	s_waitcnt lgkmcnt(0)
	v_add_f32_e32 v40, v39, v40
	v_cndmask_b32_e64 v39, 0, 1, vcc
	v_cmp_gt_f32_e32 vcc, v70, v36
	s_nop 1
	v_cndmask_b32_e32 v36, v36, v70, vcc
	v_cndmask_b32_e64 v39, v39, 2, vcc
	v_cmp_gt_f32_e32 vcc, v42, v36
	s_nop 1
	v_cndmask_b32_e32 v36, v36, v42, vcc
	v_cndmask_b32_e64 v39, v39, 3, vcc
	v_cmp_gt_f32_e32 vcc, v43, v36
	s_nop 1
	v_cndmask_b32_e32 v36, v36, v43, vcc
	v_cndmask_b32_e64 v39, v39, 4, vcc
	v_cmp_gt_f32_e32 vcc, v37, v36
	s_nop 1
	v_cndmask_b32_e32 v36, v36, v37, vcc
	v_cndmask_b32_e64 v41, v39, 5, vcc
	v_cmp_gt_f32_e32 vcc, v40, v36
	s_nop 1
	v_cndmask_b32_e32 v39, v36, v40, vcc
	v_cndmask_b32_e64 v36, v41, 6, vcc
	v_cmp_gt_f32_e64 s[6:7], v38, v39
	v_cmp_ngt_f32_e64 s[20:21], v38, v39
	s_nop 0
	v_cndmask_b32_e64 v36, v36, 7, s[6:7]
	v_cmp_eq_u32_e64 s[8:9], 0, v36
	s_or_b64 s[10:11], s[8:9], s[10:11]
	v_cndmask_b32_e64 v41, v69, v98, s[10:11]
	v_cmp_eq_u32_e64 s[10:11], 1, v36
	v_cmp_ngt_f32_e64 s[12:13], v68, v41
	s_or_b64 s[12:13], s[10:11], s[12:13]
	s_nop 0
	v_cndmask_b32_e64 v41, v68, v41, s[12:13]
	s_xor_b64 s[12:13], s[12:13], -1
	v_cndmask_b32_e64 v44, 0, 1, s[12:13]
	v_cmp_eq_u32_e64 s[12:13], 2, v36
	v_cmp_ngt_f32_e64 s[14:15], v70, v41
	s_or_b64 s[14:15], s[12:13], s[14:15]
	s_nop 0
	v_cndmask_b32_e64 v41, v70, v41, s[14:15]
	v_cndmask_b32_e64 v44, 2, v44, s[14:15]
	v_cmp_eq_u32_e64 s[14:15], 3, v36
	v_cmp_ngt_f32_e64 s[16:17], v42, v41
	s_or_b64 s[16:17], s[14:15], s[16:17]
	s_nop 0
	v_cndmask_b32_e64 v41, v42, v41, s[16:17]
	v_cndmask_b32_e64 v42, 3, v44, s[16:17]
	v_cmp_eq_u32_e64 s[16:17], 4, v36
	v_cmp_ngt_f32_e64 s[18:19], v43, v41
	s_or_b64 s[18:19], s[16:17], s[18:19]
	s_nop 0
	v_cndmask_b32_e64 v41, v43, v41, s[18:19]
	v_cndmask_b32_e64 v42, 4, v42, s[18:19]
	v_cmp_eq_u32_e64 s[18:19], 5, v36
	v_cmp_ngt_f32_e64 s[24:25], v37, v41
	s_or_b64 s[24:25], s[18:19], s[24:25]
	s_nop 0
	v_cndmask_b32_e64 v37, v37, v41, s[24:25]
	v_cndmask_b32_e64 v41, 5, v42, s[24:25]
	s_and_b64 s[24:25], vcc, s[20:21]
	v_cmp_ngt_f32_e32 vcc, v40, v37
	s_or_b64 vcc, s[24:25], vcc
	s_nop 0
	v_cndmask_b32_e32 v40, v40, v37, vcc
	v_cndmask_b32_e32 v37, 6, v41, vcc
	v_cmp_ngt_f32_e32 vcc, v38, v40
	s_or_b64 s[20:21], s[6:7], vcc
	v_cndmask_b32_e64 v37, 7, v37, s[20:21]
	s_and_saveexec_b64 s[40:41], s[2:3]
	s_cbranch_execz .LBB0_4581
	v_cndmask_b32_e64 v40, v38, v40, s[20:21]
	v_cndmask_b32_e64 v38, v39, v38, s[6:7]
	v_sub_f32_e32 v38, v40, v38
	v_mul_f32_e32 v39, 0x3fb8aa3b, v38
	v_fma_f32 v40, v38, s45, -v39
	v_rndne_f32_e32 v41, v39
	v_fmac_f32_e32 v40, 0x32a5705f, v38
	v_sub_f32_e32 v39, v39, v41
	v_add_f32_e32 v39, v39, v40
	v_exp_f32_e32 v39, v39
	v_cvt_i32_f32_e32 v40, v41
	v_cmp_ngt_f32_e32 vcc, s46, v38
	v_ldexp_f32 v39, v39, v40
	s_nop 0
	v_cndmask_b32_e32 v39, 0, v39, vcc
	v_cmp_nlt_f32_e32 vcc, s47, v38
	s_nop 1
	v_cndmask_b32_e32 v38, v99, v39, vcc
	v_add_f32_e32 v39, 1.0, v38
	v_div_scale_f32 v40, s[50:51], v39, v39, v38
	v_rcp_f32_e32 v41, v40
	s_nop 0
	v_fma_f32 v42, -v40, v41, 1.0
	v_fmac_f32_e32 v41, v42, v41
	v_div_scale_f32 v42, vcc, v38, v39, v38
	v_mul_f32_e32 v43, v42, v41
	v_fma_f32 v44, -v40, v43, v42
	v_fmac_f32_e32 v43, v44, v41
	v_fma_f32 v40, -v40, v43, v42
	v_div_scale_f32 v42, s[50:51], v39, v39, 1.0
	v_rcp_f32_e32 v44, v42
	v_div_fmas_f32 v40, v40, v41, v43
	v_div_fixup_f32 v45, v40, v39, v38
	v_fma_f32 v38, -v42, v44, 1.0
	v_fmac_f32_e32 v44, v38, v44
	v_div_scale_f32 v38, vcc, 1.0, v39, 1.0
	v_mul_f32_e32 v40, v38, v44
	v_fma_f32 v41, -v42, v40, v38
	v_fmac_f32_e32 v40, v41, v44
	v_fma_f32 v38, -v42, v40, v38
	v_div_fmas_f32 v38, v38, v44, v40
	v_div_fixup_f32 v44, v38, v39, 1.0
	v_lshlrev_b64 v[38:39], 2, v[34:35]
	v_add_u32_e32 v42, 1, v34
	v_lshl_add_u64 v[40:41], s[26:27], 0, v[38:39]
	v_ashrrev_i32_e32 v43, 31, v42
	v_lshl_add_u64 v[38:39], s[30:31], 0, v[38:39]
	global_store_dword v[38:39], v44, off
	v_lshl_add_u64 v[38:39], v[42:43], 2, s[30:31]
	global_store_dwordx2 v[40:41], v[36:37], off
	global_store_dword v[38:39], v45, off
	s_branch .LBB0_4581
